# first K-iteration after a tile epilogue counts the epilogue's stores into its vmcnt waits (stores drain during the next tile instead of stalling it)
# baseline (speedup 1.0000x reference)
.LBB0_127:
	s_lshl_b32 s6, s6, 5
	s_and_b32 s13, s6, 0x60
	s_lshl_b32 s12, s5, 13
	s_lshl_b32 s14, s13, 7
	s_add_u32 s6, s33, 0x9800000
	s_mov_b64 s[8:9], 0x80
	s_addc_u32 s7, s34, 0
	s_add_i32 m0, s19, 0x18000
	v_lshl_add_u64 v[6:7], v[6:7], 0, s[8:9]
	s_waitcnt vmcnt(4)
	s_mov_b32 s94, 0
	s_barrier
	global_load_lds_dwordx4 v[6:7], off
	v_lshl_add_u64 v[4:5], v[4:5], 0, s[8:9]
	s_add_i32 m0, s19, 0x1a000
	s_add_i32 s45, s19, 0x8000
	s_add_i32 s46, s19, 0xa000
	global_load_lds_dwordx4 v[4:5], off
	v_lshl_add_u64 v[2:3], v[2:3], 0, s[8:9]
	s_mov_b32 m0, s45
	s_add_u32 s10, s26, 0x40080
	global_load_lds_dwordx4 v[2:3], off
	v_lshl_add_u64 v[0:1], v[0:1], 0, s[8:9]
	s_mov_b32 m0, s46
	s_addc_u32 s11, s27, 0
	global_load_lds_dwordx4 v[0:1], off
	s_add_i32 m0, s19, 0x1c000
	v_lshl_add_u64 v[0:1], s[10:11], 0, v[132:133]
	global_load_lds_dwordx4 v[0:1], off
	v_lshl_add_u64 v[0:1], s[10:11], 0, v[128:129]
	s_add_i32 m0, s19, 0x1e000
	s_sext_i32_i16 s52, s4
	global_load_lds_dwordx4 v[0:1], off
	v_lshrrev_b32_e32 v1, 1, v146
	v_and_b32_e32 v1, 24, v1
	s_lshl_b32 s4, s5, 8
	v_and_b32_e32 v0, 15, v146
	v_lshlrev_b32_e32 v2, 1, v1
	s_add_i32 s4, s4, 0
	v_lshl_or_b32 v144, s5, 6, v0
	v_lshl_or_b32 v2, v0, 6, v2
	v_lshlrev_b32_e32 v0, 2, v0
	s_add_i32 s4, s4, 0x20000
	v_and_b32_e32 v3, 32, v0
	v_add_u32_e32 v147, s4, v0
	v_lshlrev_b32_e32 v0, 14, v12
	v_and_b32_e32 v0, 0xffff8000, v0
	v_or_b32_e32 v148, s13, v1
	v_lshl_add_u32 v0, v11, 11, v0
	v_and_b32_e32 v1, 1, v12
	v_lshl_or_b32 v0, v1, 6, v0
	v_lshl_add_u32 v136, v13, 1, v0
	v_lshlrev_b32_e32 v0, 14, v8
	v_and_b32_e32 v0, 0xffff8000, v0
	s_waitcnt vmcnt(6)
	v_lshl_add_u32 v0, v9, 11, v0
	v_and_b32_e32 v1, 1, v8
	v_bitop3_b32 v4, v2, s12, v3 bitop3:0xde
	v_bitop3_b32 v145, s14, v2, v3 bitop3:0xf6
	v_lshl_or_b32 v0, v1, 6, v0
	s_add_i32 s47, 0, 0x10000
	s_add_i32 s48, 0, 0x14000
	v_mov_b32_e32 v137, v133
	v_lshl_add_u32 v138, v10, 1, v0
	v_mov_b32_e32 v139, v133
	v_mov_b64_e32 v[140:141], 0x1080
	v_mov_b64_e32 v[142:143], 0x107f
	v_add_u32_e32 v149, s47, v145
	v_add_u32_e32 v150, 0, v4
	v_add_u32_e32 v151, s48, v145
	s_movk_i32 s49, 0x1600
	s_barrier

.Lg131_noy:
	ds_read_b128 v[152:155], v149
	ds_read_b128 v[156:159], v149 offset:1024
	ds_read_b128 v[160:163], v149 offset:2048
	ds_read_b128 v[164:167], v149 offset:3072
	s_add_u32 s26, s20, 0xfffc0080
	s_addc_u32 s27, s21, -1
	s_cmp_eq_u32 s57, 12
	s_cselect_b32 s29, s13, s27
	s_cselect_b32 s28, s53, s26
	s_cselect_b32 s27, s11, s56
	s_cselect_b32 s26, s54, s55
	s_add_i32 m0, s19, 0xc000
	ds_read_b128 v[168:171], v150
	ds_read_b128 v[172:175], v150 offset:1024
	ds_read_b128 v[176:179], v150 offset:2048
	ds_read_b128 v[180:183], v150 offset:3072
	ds_read_b128 v[184:187], v150 offset:4096
	ds_read_b128 v[188:191], v150 offset:5120
	ds_read_b128 v[192:195], v150 offset:6144
	ds_read_b128 v[196:199], v150 offset:7168
	global_load_lds_dwordx4 v136, s[20:21]
	s_add_i32 m0, s19, 0xe000
	s_nop 0
	global_load_lds_dwordx4 v138, s[20:21]
	s_waitcnt lgkmcnt(8)
	s_barrier
	s_waitcnt lgkmcnt(0)
	s_waitcnt lgkmcnt(0)
	v_mfma_f32_16x16x32_bf16 v[124:127], v[152:155], v[168:171], 0
	v_mfma_f32_16x16x32_bf16 v[120:123], v[160:163], v[168:171], 0
	v_mfma_f32_16x16x32_bf16 v[108:111], v[152:155], v[176:179], 0
	v_mfma_f32_16x16x32_bf16 v[104:107], v[160:163], v[176:179], 0
	v_mfma_f32_16x16x32_bf16 v[92:95], v[152:155], v[184:187], 0
	v_mfma_f32_16x16x32_bf16 v[88:91], v[160:163], v[184:187], 0
	v_mfma_f32_16x16x32_bf16 v[76:79], v[152:155], v[192:195], 0
	v_mfma_f32_16x16x32_bf16 v[72:75], v[160:163], v[192:195], 0
	v_mfma_f32_16x16x32_bf16 v[124:127], v[156:159], v[172:175], v[124:127]
	v_mfma_f32_16x16x32_bf16 v[120:123], v[164:167], v[172:175], v[120:123]
	v_mfma_f32_16x16x32_bf16 v[108:111], v[156:159], v[180:183], v[108:111]
	v_mfma_f32_16x16x32_bf16 v[104:107], v[164:167], v[180:183], v[104:107]
	v_mfma_f32_16x16x32_bf16 v[92:95], v[156:159], v[188:191], v[92:95]
	v_mfma_f32_16x16x32_bf16 v[88:91], v[164:167], v[188:191], v[88:91]
	v_mfma_f32_16x16x32_bf16 v[76:79], v[156:159], v[196:199], v[76:79]
	v_mfma_f32_16x16x32_bf16 v[72:75], v[164:167], v[196:199], v[72:75]
	s_barrier
	s_add_i32 s58, s47, s38
	s_add_u32 s80, s26, 0x80
	s_addc_u32 s81, s27, 0
	s_mov_b32 m0, s58
	ds_read_b128 v[200:203], v151
	ds_read_b128 v[204:207], v151 offset:1024
	ds_read_b128 v[208:211], v151 offset:2048
	ds_read_b128 v[212:215], v151 offset:3072
	global_load_lds_dwordx4 v132, s[26:27]
	s_add_i32 m0, s58, 0x2000
	s_nop 0
	global_load_lds_dwordx4 v128, s[26:27]
	s_cmp_lg_u32 s94, 0
	s_cbranch_scc1 .Lpw131_0a
	s_waitcnt vmcnt(10)
	s_branch .Lpw131_0b
.Lpw131_0a:
	s_waitcnt vmcnt(18)
.Lpw131_0b:
	s_barrier
	s_waitcnt lgkmcnt(0)
	s_waitcnt lgkmcnt(0)
	v_mfma_f32_16x16x32_bf16 v[116:119], v[200:203], v[168:171], 0
	v_mfma_f32_16x16x32_bf16 v[112:115], v[208:211], v[168:171], 0
	v_mfma_f32_16x16x32_bf16 v[100:103], v[200:203], v[176:179], 0
	v_mfma_f32_16x16x32_bf16 v[96:99], v[208:211], v[176:179], 0
	v_mfma_f32_16x16x32_bf16 v[84:87], v[200:203], v[184:187], 0
	v_mfma_f32_16x16x32_bf16 v[80:83], v[208:211], v[184:187], 0
	v_mfma_f32_16x16x32_bf16 v[68:71], v[200:203], v[192:195], 0
	v_mfma_f32_16x16x32_bf16 v[64:67], v[208:211], v[192:195], 0
	v_mfma_f32_16x16x32_bf16 v[116:119], v[204:207], v[172:175], v[116:119]
	v_mfma_f32_16x16x32_bf16 v[112:115], v[212:215], v[172:175], v[112:115]
	v_mfma_f32_16x16x32_bf16 v[100:103], v[204:207], v[180:183], v[100:103]
	v_mfma_f32_16x16x32_bf16 v[96:99], v[212:215], v[180:183], v[96:99]
	v_mfma_f32_16x16x32_bf16 v[84:87], v[204:207], v[188:191], v[84:87]
	v_mfma_f32_16x16x32_bf16 v[80:83], v[212:215], v[188:191], v[80:83]
	v_mfma_f32_16x16x32_bf16 v[68:71], v[204:207], v[196:199], v[68:71]
	v_mfma_f32_16x16x32_bf16 v[64:67], v[212:215], v[196:199], v[64:67]
	s_mov_b32 m0, s19
	s_add_u32 s82, s28, 0x80
	s_addc_u32 s83, s29, 0
	s_barrier
	ds_read_b128 v[168:171], v150 offset:16384
	ds_read_b128 v[172:175], v150 offset:17408
	ds_read_b128 v[176:179], v150 offset:18432
	ds_read_b128 v[180:183], v150 offset:19456
	ds_read_b128 v[184:187], v150 offset:20480
	ds_read_b128 v[188:191], v150 offset:21504
	ds_read_b128 v[192:195], v150 offset:22528
	ds_read_b128 v[196:199], v150 offset:23552
	global_load_lds_dwordx4 v134, s[28:29]
	s_mov_b32 m0, s42
	s_nop 0
	global_load_lds_dwordx4 v130, s[28:29]
	s_barrier
	s_waitcnt lgkmcnt(0)
	s_waitcnt lgkmcnt(0)
	v_mfma_f32_16x16x32_bf16 v[60:63], v[152:155], v[168:171], 0
	v_mfma_f32_16x16x32_bf16 v[56:59], v[160:163], v[168:171], 0
	v_mfma_f32_16x16x32_bf16 v[44:47], v[152:155], v[176:179], 0
	v_mfma_f32_16x16x32_bf16 v[40:43], v[160:163], v[176:179], 0
	v_mfma_f32_16x16x32_bf16 v[28:31], v[152:155], v[184:187], 0
	v_mfma_f32_16x16x32_bf16 v[24:27], v[160:163], v[184:187], 0
	v_mfma_f32_16x16x32_bf16 v[12:15], v[152:155], v[192:195], 0
	v_mfma_f32_16x16x32_bf16 v[8:11], v[160:163], v[192:195], 0
	v_mfma_f32_16x16x32_bf16 v[60:63], v[156:159], v[172:175], v[60:63]
	v_mfma_f32_16x16x32_bf16 v[56:59], v[164:167], v[172:175], v[56:59]
	v_mfma_f32_16x16x32_bf16 v[44:47], v[156:159], v[180:183], v[44:47]
	v_mfma_f32_16x16x32_bf16 v[40:43], v[164:167], v[180:183], v[40:43]
	v_mfma_f32_16x16x32_bf16 v[28:31], v[156:159], v[188:191], v[28:31]
	v_mfma_f32_16x16x32_bf16 v[24:27], v[164:167], v[188:191], v[24:27]
	v_mfma_f32_16x16x32_bf16 v[12:15], v[156:159], v[196:199], v[12:15]
	v_mfma_f32_16x16x32_bf16 v[8:11], v[164:167], v[196:199], v[8:11]
	s_barrier
	s_add_u32 s58, s26, 0x40000
	s_addc_u32 s59, s27, 0
	s_add_i32 s60, s48, s38
	s_mov_b32 m0, s60
	s_nop 0
	global_load_lds_dwordx4 v132, s[58:59]
	s_add_i32 m0, s60, 0x2000
	s_nop 0
	global_load_lds_dwordx4 v128, s[58:59]
	s_cmp_lg_u32 s94, 0
	s_cbranch_scc1 .Lpw131_1a
	s_waitcnt vmcnt(8)
	s_branch .Lpw131_1b
.Lpw131_1a:
	s_waitcnt vmcnt(16)
.Lpw131_1b:
	s_barrier
	v_mfma_f32_16x16x32_bf16 v[52:55], v[200:203], v[168:171], 0
	v_mfma_f32_16x16x32_bf16 v[48:51], v[208:211], v[168:171], 0
	v_mfma_f32_16x16x32_bf16 v[36:39], v[200:203], v[176:179], 0
	v_mfma_f32_16x16x32_bf16 v[32:35], v[208:211], v[176:179], 0
	v_mfma_f32_16x16x32_bf16 v[20:23], v[200:203], v[184:187], 0
	v_mfma_f32_16x16x32_bf16 v[16:19], v[208:211], v[184:187], 0
	v_mfma_f32_16x16x32_bf16 v[4:7], v[200:203], v[192:195], 0
	v_mfma_f32_16x16x32_bf16 v[0:3], v[208:211], v[192:195], 0
	v_mfma_f32_16x16x32_bf16 v[52:55], v[204:207], v[172:175], v[52:55]
	v_mfma_f32_16x16x32_bf16 v[48:51], v[212:215], v[172:175], v[48:51]
	v_mfma_f32_16x16x32_bf16 v[36:39], v[204:207], v[180:183], v[36:39]
	v_mfma_f32_16x16x32_bf16 v[32:35], v[212:215], v[180:183], v[32:35]
	v_mfma_f32_16x16x32_bf16 v[20:23], v[204:207], v[188:191], v[20:23]
	v_mfma_f32_16x16x32_bf16 v[16:19], v[212:215], v[188:191], v[16:19]
	v_mfma_f32_16x16x32_bf16 v[4:7], v[204:207], v[196:199], v[4:7]
	v_mfma_f32_16x16x32_bf16 v[0:3], v[212:215], v[196:199], v[0:3]
	s_add_i32 s58, 0, 0x18000
	v_add_u32_e32 v164, s58, v145
	s_barrier
	s_branch .Lg131_mid

.Lg131_nox:
	s_mov_b32 s94, 1
	v_lshl_add_u32 v180, s51, 10, v147
	ds_read2_b32 v[152:153], v180 offset1:16
	ds_read2_b32 v[154:155], v180 offset0:32 offset1:48
	ds_read2_b32 v[156:157], v180 offset0:128 offset1:144
	ds_read2_b32 v[158:159], v180 offset0:160 offset1:176
	v_lshl_or_b32 v181, s52, 7, v148
	v_lshl_add_u32 v182, s18, 8, v144
	s_and_b64 vcc, exec, s[4:5]
	s_mov_b32 s52, s10
	s_mov_b32 s18, s12
	s_mov_b64 s[26:27], s[16:17]
	s_mov_b32 s51, s50
	s_mov_b64 s[20:21], s[14:15]
	v_mul_u32_u24_e32 v183, s49, v182
	v_lshl_add_u32 v183, v181, 1, v183
	s_waitcnt lgkmcnt(0)
	v_mul_f32_e32 v176, 0xbfb8aa3b, v152
	v_mul_f32_e32 v177, v152, v152
	v_rcp_f32_e32 v178, v177
	v_pk_mul_f32 v[160:161], v[124:125], v[176:177] op_sel_hi:[1,0]
	v_pk_mul_f32 v[162:163], v[126:127], v[176:177] op_sel_hi:[1,0]
	v_pk_mul_f32 v[164:165], v[120:121], v[176:177] op_sel_hi:[1,0]
	v_pk_mul_f32 v[166:167], v[122:123], v[176:177] op_sel_hi:[1,0]
	v_exp_f32_e32 v160, v160
	v_exp_f32_e32 v161, v161
	v_exp_f32_e32 v162, v162
	v_exp_f32_e32 v163, v163
	v_exp_f32_e32 v164, v164
	v_exp_f32_e32 v165, v165
	v_exp_f32_e32 v166, v166
	v_exp_f32_e32 v167, v167
	v_pk_fma_f32 v[160:161], v[160:161], v[178:179], v[178:179] op_sel_hi:[1,0,0]
	v_pk_fma_f32 v[162:163], v[162:163], v[178:179], v[178:179] op_sel_hi:[1,0,0]
	v_pk_fma_f32 v[164:165], v[164:165], v[178:179], v[178:179] op_sel_hi:[1,0,0]
	v_pk_fma_f32 v[166:167], v[166:167], v[178:179], v[178:179] op_sel_hi:[1,0,0]
	v_rcp_f32_e32 v160, v160
	v_rcp_f32_e32 v161, v161
	v_rcp_f32_e32 v162, v162
	v_rcp_f32_e32 v163, v163
	v_rcp_f32_e32 v164, v164
	v_rcp_f32_e32 v165, v165
	v_rcp_f32_e32 v166, v166
	v_rcp_f32_e32 v167, v167
	v_pk_mul_f32 v[124:125], v[124:125], v[116:117]
	v_pk_mul_f32 v[126:127], v[126:127], v[118:119]
	v_pk_mul_f32 v[120:121], v[120:121], v[112:113]
	v_pk_mul_f32 v[122:123], v[122:123], v[114:115]
	v_pk_mul_f32 v[124:125], v[124:125], v[160:161]
	v_pk_mul_f32 v[126:127], v[126:127], v[162:163]
	v_pk_mul_f32 v[120:121], v[120:121], v[164:165]
	v_pk_mul_f32 v[122:123], v[122:123], v[166:167]
	v_cvt_pk_bf16_f32 v168, v124, v125
	v_cvt_pk_bf16_f32 v169, v126, v127
	v_cvt_pk_bf16_f32 v170, v120, v121
	v_cvt_pk_bf16_f32 v171, v122, v123
	global_store_dwordx4 v183, v[168:171], s[6:7]
	v_mul_f32_e32 v176, 0xbfb8aa3b, v153
	v_mul_f32_e32 v177, v153, v153
	v_rcp_f32_e32 v178, v177
	v_pk_mul_f32 v[160:161], v[108:109], v[176:177] op_sel_hi:[1,0]
	v_pk_mul_f32 v[162:163], v[110:111], v[176:177] op_sel_hi:[1,0]
	v_pk_mul_f32 v[164:165], v[104:105], v[176:177] op_sel_hi:[1,0]
	v_pk_mul_f32 v[166:167], v[106:107], v[176:177] op_sel_hi:[1,0]
	v_exp_f32_e32 v160, v160
	v_exp_f32_e32 v161, v161
	v_exp_f32_e32 v162, v162
	v_exp_f32_e32 v163, v163
	v_exp_f32_e32 v164, v164
	v_exp_f32_e32 v165, v165
	v_exp_f32_e32 v166, v166
	v_exp_f32_e32 v167, v167
	v_pk_fma_f32 v[160:161], v[160:161], v[178:179], v[178:179] op_sel_hi:[1,0,0]
	v_pk_fma_f32 v[162:163], v[162:163], v[178:179], v[178:179] op_sel_hi:[1,0,0]
	v_pk_fma_f32 v[164:165], v[164:165], v[178:179], v[178:179] op_sel_hi:[1,0,0]
	v_pk_fma_f32 v[166:167], v[166:167], v[178:179], v[178:179] op_sel_hi:[1,0,0]
	v_rcp_f32_e32 v160, v160
	v_rcp_f32_e32 v161, v161
	v_rcp_f32_e32 v162, v162
	v_rcp_f32_e32 v163, v163
	v_rcp_f32_e32 v164, v164
	v_rcp_f32_e32 v165, v165
	v_rcp_f32_e32 v166, v166
	v_rcp_f32_e32 v167, v167
	v_pk_mul_f32 v[108:109], v[108:109], v[100:101]
	v_pk_mul_f32 v[110:111], v[110:111], v[102:103]
	v_pk_mul_f32 v[104:105], v[104:105], v[96:97]
	v_pk_mul_f32 v[106:107], v[106:107], v[98:99]
	v_pk_mul_f32 v[108:109], v[108:109], v[160:161]
	v_pk_mul_f32 v[110:111], v[110:111], v[162:163]
	v_pk_mul_f32 v[104:105], v[104:105], v[164:165]
	v_pk_mul_f32 v[106:107], v[106:107], v[166:167]
	v_cvt_pk_bf16_f32 v172, v108, v109
	v_cvt_pk_bf16_f32 v173, v110, v111
	v_cvt_pk_bf16_f32 v174, v104, v105
	v_cvt_pk_bf16_f32 v175, v106, v107
	v_add_u32_e32 v185, 0x16000, v183
	global_store_dwordx4 v185, v[172:175], s[6:7]
	v_mul_f32_e32 v176, 0xbfb8aa3b, v154
	v_mul_f32_e32 v177, v154, v154
	v_rcp_f32_e32 v178, v177
	v_pk_mul_f32 v[160:161], v[92:93], v[176:177] op_sel_hi:[1,0]
	v_pk_mul_f32 v[162:163], v[94:95], v[176:177] op_sel_hi:[1,0]
	v_pk_mul_f32 v[164:165], v[88:89], v[176:177] op_sel_hi:[1,0]
	v_pk_mul_f32 v[166:167], v[90:91], v[176:177] op_sel_hi:[1,0]
	v_exp_f32_e32 v160, v160
	v_exp_f32_e32 v161, v161
	v_exp_f32_e32 v162, v162
	v_exp_f32_e32 v163, v163
	v_exp_f32_e32 v164, v164
	v_exp_f32_e32 v165, v165
	v_exp_f32_e32 v166, v166
	v_exp_f32_e32 v167, v167
	v_pk_fma_f32 v[160:161], v[160:161], v[178:179], v[178:179] op_sel_hi:[1,0,0]
	v_pk_fma_f32 v[162:163], v[162:163], v[178:179], v[178:179] op_sel_hi:[1,0,0]
	v_pk_fma_f32 v[164:165], v[164:165], v[178:179], v[178:179] op_sel_hi:[1,0,0]
	v_pk_fma_f32 v[166:167], v[166:167], v[178:179], v[178:179] op_sel_hi:[1,0,0]
	v_rcp_f32_e32 v160, v160
	v_rcp_f32_e32 v161, v161
	v_rcp_f32_e32 v162, v162
	v_rcp_f32_e32 v163, v163
	v_rcp_f32_e32 v164, v164
	v_rcp_f32_e32 v165, v165
	v_rcp_f32_e32 v166, v166
	v_rcp_f32_e32 v167, v167
	v_pk_mul_f32 v[92:93], v[92:93], v[84:85]
	v_pk_mul_f32 v[94:95], v[94:95], v[86:87]
	v_pk_mul_f32 v[88:89], v[88:89], v[80:81]
	v_pk_mul_f32 v[90:91], v[90:91], v[82:83]
	v_pk_mul_f32 v[92:93], v[92:93], v[160:161]
	v_pk_mul_f32 v[94:95], v[94:95], v[162:163]
	v_pk_mul_f32 v[88:89], v[88:89], v[164:165]
	v_pk_mul_f32 v[90:91], v[90:91], v[166:167]
	v_cvt_pk_bf16_f32 v168, v92, v93
	v_cvt_pk_bf16_f32 v169, v94, v95
	v_cvt_pk_bf16_f32 v170, v88, v89
	v_cvt_pk_bf16_f32 v171, v90, v91
	v_add_u32_e32 v184, 0x2c000, v183
	global_store_dwordx4 v184, v[168:171], s[6:7]
	v_mul_f32_e32 v176, 0xbfb8aa3b, v155
	v_mul_f32_e32 v177, v155, v155
	v_rcp_f32_e32 v178, v177
	v_pk_mul_f32 v[160:161], v[76:77], v[176:177] op_sel_hi:[1,0]
	v_pk_mul_f32 v[162:163], v[78:79], v[176:177] op_sel_hi:[1,0]
	v_pk_mul_f32 v[164:165], v[72:73], v[176:177] op_sel_hi:[1,0]
	v_pk_mul_f32 v[166:167], v[74:75], v[176:177] op_sel_hi:[1,0]
	v_exp_f32_e32 v160, v160
	v_exp_f32_e32 v161, v161
	v_exp_f32_e32 v162, v162
	v_exp_f32_e32 v163, v163
	v_exp_f32_e32 v164, v164
	v_exp_f32_e32 v165, v165
	v_exp_f32_e32 v166, v166
	v_exp_f32_e32 v167, v167
	v_pk_fma_f32 v[160:161], v[160:161], v[178:179], v[178:179] op_sel_hi:[1,0,0]
	v_pk_fma_f32 v[162:163], v[162:163], v[178:179], v[178:179] op_sel_hi:[1,0,0]
	v_pk_fma_f32 v[164:165], v[164:165], v[178:179], v[178:179] op_sel_hi:[1,0,0]
	v_pk_fma_f32 v[166:167], v[166:167], v[178:179], v[178:179] op_sel_hi:[1,0,0]
	v_rcp_f32_e32 v160, v160
	v_rcp_f32_e32 v161, v161
	v_rcp_f32_e32 v162, v162
	v_rcp_f32_e32 v163, v163
	v_rcp_f32_e32 v164, v164
	v_rcp_f32_e32 v165, v165
	v_rcp_f32_e32 v166, v166
	v_rcp_f32_e32 v167, v167
	v_pk_mul_f32 v[76:77], v[76:77], v[68:69]
	v_pk_mul_f32 v[78:79], v[78:79], v[70:71]
	v_pk_mul_f32 v[72:73], v[72:73], v[64:65]
	v_pk_mul_f32 v[74:75], v[74:75], v[66:67]
	v_pk_mul_f32 v[76:77], v[76:77], v[160:161]
	v_pk_mul_f32 v[78:79], v[78:79], v[162:163]
	v_pk_mul_f32 v[72:73], v[72:73], v[164:165]
	v_pk_mul_f32 v[74:75], v[74:75], v[166:167]
	v_cvt_pk_bf16_f32 v172, v76, v77
	v_cvt_pk_bf16_f32 v173, v78, v79
	v_cvt_pk_bf16_f32 v174, v72, v73
	v_cvt_pk_bf16_f32 v175, v74, v75
	v_add_u32_e32 v185, 0x42000, v183
	global_store_dwordx4 v185, v[172:175], s[6:7]
	v_mul_f32_e32 v176, 0xbfb8aa3b, v156
	v_mul_f32_e32 v177, v156, v156
	v_rcp_f32_e32 v178, v177
	v_pk_mul_f32 v[160:161], v[60:61], v[176:177] op_sel_hi:[1,0]
	v_pk_mul_f32 v[162:163], v[62:63], v[176:177] op_sel_hi:[1,0]
	v_pk_mul_f32 v[164:165], v[56:57], v[176:177] op_sel_hi:[1,0]
	v_pk_mul_f32 v[166:167], v[58:59], v[176:177] op_sel_hi:[1,0]
	v_exp_f32_e32 v160, v160
	v_exp_f32_e32 v161, v161
	v_exp_f32_e32 v162, v162
	v_exp_f32_e32 v163, v163
	v_exp_f32_e32 v164, v164
	v_exp_f32_e32 v165, v165
	v_exp_f32_e32 v166, v166
	v_exp_f32_e32 v167, v167
	v_pk_fma_f32 v[160:161], v[160:161], v[178:179], v[178:179] op_sel_hi:[1,0,0]
	v_pk_fma_f32 v[162:163], v[162:163], v[178:179], v[178:179] op_sel_hi:[1,0,0]
	v_pk_fma_f32 v[164:165], v[164:165], v[178:179], v[178:179] op_sel_hi:[1,0,0]
	v_pk_fma_f32 v[166:167], v[166:167], v[178:179], v[178:179] op_sel_hi:[1,0,0]
	v_rcp_f32_e32 v160, v160
	v_rcp_f32_e32 v161, v161
	v_rcp_f32_e32 v162, v162
	v_rcp_f32_e32 v163, v163
	v_rcp_f32_e32 v164, v164
	v_rcp_f32_e32 v165, v165
	v_rcp_f32_e32 v166, v166
	v_rcp_f32_e32 v167, v167
	v_pk_mul_f32 v[60:61], v[60:61], v[52:53]
	v_pk_mul_f32 v[62:63], v[62:63], v[54:55]
	v_pk_mul_f32 v[56:57], v[56:57], v[48:49]
	v_pk_mul_f32 v[58:59], v[58:59], v[50:51]
	v_pk_mul_f32 v[60:61], v[60:61], v[160:161]
	v_pk_mul_f32 v[62:63], v[62:63], v[162:163]
	v_pk_mul_f32 v[56:57], v[56:57], v[164:165]
	v_pk_mul_f32 v[58:59], v[58:59], v[166:167]
	v_cvt_pk_bf16_f32 v168, v60, v61
	v_cvt_pk_bf16_f32 v169, v62, v63
	v_cvt_pk_bf16_f32 v170, v56, v57
	v_cvt_pk_bf16_f32 v171, v58, v59
	v_add_u32_e32 v184, 0xb0000, v183
	global_store_dwordx4 v184, v[168:171], s[6:7]
	v_mul_f32_e32 v176, 0xbfb8aa3b, v157
	v_mul_f32_e32 v177, v157, v157
	v_rcp_f32_e32 v178, v177
	v_pk_mul_f32 v[160:161], v[44:45], v[176:177] op_sel_hi:[1,0]
	v_pk_mul_f32 v[162:163], v[46:47], v[176:177] op_sel_hi:[1,0]
	v_pk_mul_f32 v[164:165], v[40:41], v[176:177] op_sel_hi:[1,0]
	v_pk_mul_f32 v[166:167], v[42:43], v[176:177] op_sel_hi:[1,0]
	v_exp_f32_e32 v160, v160
	v_exp_f32_e32 v161, v161
	v_exp_f32_e32 v162, v162
	v_exp_f32_e32 v163, v163
	v_exp_f32_e32 v164, v164
	v_exp_f32_e32 v165, v165
	v_exp_f32_e32 v166, v166
	v_exp_f32_e32 v167, v167
	v_pk_fma_f32 v[160:161], v[160:161], v[178:179], v[178:179] op_sel_hi:[1,0,0]
	v_pk_fma_f32 v[162:163], v[162:163], v[178:179], v[178:179] op_sel_hi:[1,0,0]
	v_pk_fma_f32 v[164:165], v[164:165], v[178:179], v[178:179] op_sel_hi:[1,0,0]
	v_pk_fma_f32 v[166:167], v[166:167], v[178:179], v[178:179] op_sel_hi:[1,0,0]
	v_rcp_f32_e32 v160, v160
	v_rcp_f32_e32 v161, v161
	v_rcp_f32_e32 v162, v162
	v_rcp_f32_e32 v163, v163
	v_rcp_f32_e32 v164, v164
	v_rcp_f32_e32 v165, v165
	v_rcp_f32_e32 v166, v166
	v_rcp_f32_e32 v167, v167
	v_pk_mul_f32 v[44:45], v[44:45], v[36:37]
	v_pk_mul_f32 v[46:47], v[46:47], v[38:39]
	v_pk_mul_f32 v[40:41], v[40:41], v[32:33]
	v_pk_mul_f32 v[42:43], v[42:43], v[34:35]
	v_pk_mul_f32 v[44:45], v[44:45], v[160:161]
	v_pk_mul_f32 v[46:47], v[46:47], v[162:163]
	v_pk_mul_f32 v[40:41], v[40:41], v[164:165]
	v_pk_mul_f32 v[42:43], v[42:43], v[166:167]
	v_cvt_pk_bf16_f32 v172, v44, v45
	v_cvt_pk_bf16_f32 v173, v46, v47
	v_cvt_pk_bf16_f32 v174, v40, v41
	v_cvt_pk_bf16_f32 v175, v42, v43
	v_add_u32_e32 v185, 0xc6000, v183
	global_store_dwordx4 v185, v[172:175], s[6:7]
	v_mul_f32_e32 v176, 0xbfb8aa3b, v158
	v_mul_f32_e32 v177, v158, v158
	v_rcp_f32_e32 v178, v177
	v_pk_mul_f32 v[160:161], v[28:29], v[176:177] op_sel_hi:[1,0]
	v_pk_mul_f32 v[162:163], v[30:31], v[176:177] op_sel_hi:[1,0]
	v_pk_mul_f32 v[164:165], v[24:25], v[176:177] op_sel_hi:[1,0]
	v_pk_mul_f32 v[166:167], v[26:27], v[176:177] op_sel_hi:[1,0]
	v_exp_f32_e32 v160, v160
	v_exp_f32_e32 v161, v161
	v_exp_f32_e32 v162, v162
	v_exp_f32_e32 v163, v163
	v_exp_f32_e32 v164, v164
	v_exp_f32_e32 v165, v165
	v_exp_f32_e32 v166, v166
	v_exp_f32_e32 v167, v167
	v_pk_fma_f32 v[160:161], v[160:161], v[178:179], v[178:179] op_sel_hi:[1,0,0]
	v_pk_fma_f32 v[162:163], v[162:163], v[178:179], v[178:179] op_sel_hi:[1,0,0]
	v_pk_fma_f32 v[164:165], v[164:165], v[178:179], v[178:179] op_sel_hi:[1,0,0]
	v_pk_fma_f32 v[166:167], v[166:167], v[178:179], v[178:179] op_sel_hi:[1,0,0]
	v_rcp_f32_e32 v160, v160
	v_rcp_f32_e32 v161, v161
	v_rcp_f32_e32 v162, v162
	v_rcp_f32_e32 v163, v163
	v_rcp_f32_e32 v164, v164
	v_rcp_f32_e32 v165, v165
	v_rcp_f32_e32 v166, v166
	v_rcp_f32_e32 v167, v167
	v_pk_mul_f32 v[28:29], v[28:29], v[20:21]
	v_pk_mul_f32 v[30:31], v[30:31], v[22:23]
	v_pk_mul_f32 v[24:25], v[24:25], v[16:17]
	v_pk_mul_f32 v[26:27], v[26:27], v[18:19]
	v_pk_mul_f32 v[28:29], v[28:29], v[160:161]
	v_pk_mul_f32 v[30:31], v[30:31], v[162:163]
	v_pk_mul_f32 v[24:25], v[24:25], v[164:165]
	v_pk_mul_f32 v[26:27], v[26:27], v[166:167]
	v_cvt_pk_bf16_f32 v168, v28, v29
	v_cvt_pk_bf16_f32 v169, v30, v31
	v_cvt_pk_bf16_f32 v170, v24, v25
	v_cvt_pk_bf16_f32 v171, v26, v27
	v_add_u32_e32 v184, 0xdc000, v183
	global_store_dwordx4 v184, v[168:171], s[6:7]
	v_mul_f32_e32 v176, 0xbfb8aa3b, v159
	v_mul_f32_e32 v177, v159, v159
	v_rcp_f32_e32 v178, v177
	v_pk_mul_f32 v[160:161], v[12:13], v[176:177] op_sel_hi:[1,0]
	v_pk_mul_f32 v[162:163], v[14:15], v[176:177] op_sel_hi:[1,0]
	v_pk_mul_f32 v[164:165], v[8:9], v[176:177] op_sel_hi:[1,0]
	v_pk_mul_f32 v[166:167], v[10:11], v[176:177] op_sel_hi:[1,0]
	v_exp_f32_e32 v160, v160
	v_exp_f32_e32 v161, v161
	v_exp_f32_e32 v162, v162
	v_exp_f32_e32 v163, v163
	v_exp_f32_e32 v164, v164
	v_exp_f32_e32 v165, v165
	v_exp_f32_e32 v166, v166
	v_exp_f32_e32 v167, v167
	v_pk_fma_f32 v[160:161], v[160:161], v[178:179], v[178:179] op_sel_hi:[1,0,0]
	v_pk_fma_f32 v[162:163], v[162:163], v[178:179], v[178:179] op_sel_hi:[1,0,0]
	v_pk_fma_f32 v[164:165], v[164:165], v[178:179], v[178:179] op_sel_hi:[1,0,0]
	v_pk_fma_f32 v[166:167], v[166:167], v[178:179], v[178:179] op_sel_hi:[1,0,0]
	v_rcp_f32_e32 v160, v160
	v_rcp_f32_e32 v161, v161
	v_rcp_f32_e32 v162, v162
	v_rcp_f32_e32 v163, v163
	v_rcp_f32_e32 v164, v164
	v_rcp_f32_e32 v165, v165
	v_rcp_f32_e32 v166, v166
	v_rcp_f32_e32 v167, v167
	v_pk_mul_f32 v[12:13], v[12:13], v[4:5]
	v_pk_mul_f32 v[14:15], v[14:15], v[6:7]
	v_pk_mul_f32 v[8:9], v[8:9], v[0:1]
	v_pk_mul_f32 v[10:11], v[10:11], v[2:3]
	v_pk_mul_f32 v[12:13], v[12:13], v[160:161]
	v_pk_mul_f32 v[14:15], v[14:15], v[162:163]
	v_pk_mul_f32 v[8:9], v[8:9], v[164:165]
	v_pk_mul_f32 v[10:11], v[10:11], v[166:167]
	v_cvt_pk_bf16_f32 v172, v12, v13
	v_cvt_pk_bf16_f32 v173, v14, v15
	v_cvt_pk_bf16_f32 v174, v8, v9
	v_cvt_pk_bf16_f32 v175, v10, v11
	v_add_u32_e32 v185, 0xf2000, v183
	global_store_dwordx4 v185, v[172:175], s[6:7]
	s_cbranch_vccz .LBB0_128
	s_waitcnt vmcnt(0)
	s_cmpk_gt_u32 s37, 0xff
	s_cbranch_scc1 .LBB0_135

.LBB0_239:
	s_add_u32 s14, s6, 0x3800000
	s_addc_u32 s15, s7, 0
	s_add_u32 s16, s6, 0x2d00000
	s_mov_b64 s[18:19], 0x80
	s_addc_u32 s17, s7, 0
	s_and_b32 s45, s4, 3
	s_add_i32 m0, s41, 0x18000
	v_lshl_add_u64 v[6:7], v[6:7], 0, s[18:19]
	s_lshl_b32 s4, s5, 13
	s_lshl_b32 s9, s45, 12
	s_waitcnt vmcnt(4)
	s_mov_b32 s94, 0
	s_barrier
	global_load_lds_dwordx4 v[6:7], off
	v_lshl_add_u64 v[4:5], v[4:5], 0, s[18:19]
	s_add_i32 m0, s41, 0x1a000
	s_add_i32 s46, s41, 0x8000
	s_add_i32 s47, s41, 0xa000
	global_load_lds_dwordx4 v[4:5], off
	v_lshl_add_u64 v[2:3], v[2:3], 0, s[18:19]
	s_mov_b32 m0, s46
	s_add_u32 s6, s26, 0xb0080
	global_load_lds_dwordx4 v[2:3], off
	v_lshl_add_u64 v[0:1], v[0:1], 0, s[18:19]
	s_mov_b32 m0, s47
	s_addc_u32 s7, s27, 0
	global_load_lds_dwordx4 v[0:1], off
	s_add_i32 m0, s41, 0x1c000
	v_lshl_add_u64 v[0:1], s[6:7], 0, v[130:131]
	global_load_lds_dwordx4 v[0:1], off
	v_lshl_add_u64 v[0:1], s[6:7], 0, v[134:135]
	s_add_i32 m0, s41, 0x1e000
	s_mov_b64 s[6:7], 0xb0080
	global_load_lds_dwordx4 v[0:1], off
	v_bfe_u32 v0, v8, 4, 2
	v_and_b32_e32 v1, 15, v8
	v_lshlrev_b32_e32 v3, 4, v0
	v_lshl_or_b32 v148, s5, 6, v1
	v_lshl_or_b32 v1, v1, 6, v3
	v_lshlrev_b32_e32 v3, 2, v8
	v_and_b32_e32 v3, 32, v3
	v_lshlrev_b32_e32 v2, 3, v0
	v_bitop3_b32 v4, v1, s4, v3 bitop3:0xde
	v_bitop3_b32 v149, s9, v1, v3 bitop3:0xf6
	v_cmp_eq_u32_e64 s[4:5], 0, v0
	v_lshrrev_b32_e32 v1, 1, v9
	v_mul_lo_u32 v0, v11, s8
	s_mov_b32 s9, 0xb000
	v_mad_u64_u32 v[0:1], s[10:11], v1, s9, v[0:1]
	v_or_b32_e32 v0, v0, v10
	v_add_lshl_u32 v0, v0, v12, 1
	v_mov_b32_e32 v1, v131
	v_lshl_add_u64 v[136:137], v[0:1], 0, s[6:7]
	v_lshrrev_b32_e32 v1, 1, v13
	v_mul_lo_u32 v0, v14, s8
	v_mad_u64_u32 v[0:1], s[8:9], v1, s9, v[0:1]
	s_waitcnt vmcnt(6)
	v_or_b32_e32 v0, v0, v15
	v_add_lshl_u32 v0, v0, v16, 1
	v_mov_b32_e32 v1, v131
	s_add_i32 s51, 0, 0x10000
	s_add_i32 s52, 0, 0x14000
	v_lshl_or_b32 v150, s45, 5, v2
	s_ashr_i32 s48, s34, 31
	s_ashr_i32 s49, s33, 31
	v_lshl_add_u64 v[138:139], v[0:1], 0, s[6:7]
	v_mov_b64_e32 v[140:141], 0x300
	v_mov_b64_e32 v[142:143], 0x2ff
	s_movk_i32 s50, 0x61
	v_add_u32_e32 v151, s51, v149
	v_add_u32_e32 v152, 0, v4
	v_add_u32_e32 v153, s52, v149
	v_mbcnt_hi_u32_b32 v154, -1, v241
	s_mov_b32 s53, 0
	s_barrier
	s_branch .LBB0_241

.Lg248_noy:
	ds_read_b128 v[144:147], v151
	ds_read_b128 v[156:159], v151 offset:1024
	ds_read_b128 v[160:163], v151 offset:2048
	ds_read_b128 v[164:167], v151 offset:3072
	s_add_u32 s26, s20, 0x100
	s_addc_u32 s27, s21, 0
	s_cmp_eq_u32 s59, 40
	s_cselect_b32 s31, s9, s27
	s_cselect_b32 s30, s8, s26
	s_cselect_b32 s29, s11, s58
	s_cselect_b32 s28, s10, s57
	s_add_i32 m0, s41, 0xc000
	ds_read_b128 v[168:171], v152
	ds_read_b128 v[172:175], v152 offset:1024
	ds_read_b128 v[176:179], v152 offset:2048
	ds_read_b128 v[180:183], v152 offset:3072
	ds_read_b128 v[184:187], v152 offset:4096
	ds_read_b128 v[188:191], v152 offset:5120
	ds_read_b128 v[192:195], v152 offset:6144
	ds_read_b128 v[196:199], v152 offset:7168
	global_load_lds_dwordx4 v136, s[20:21]
	s_add_i32 m0, s41, 0xe000
	s_nop 0
	global_load_lds_dwordx4 v138, s[20:21]
	s_waitcnt lgkmcnt(8)
	s_barrier
	s_waitcnt lgkmcnt(0)
	s_waitcnt lgkmcnt(0)
	v_mfma_f32_16x16x32_bf16 v[124:127], v[144:147], v[168:171], 0
	v_mfma_f32_16x16x32_bf16 v[120:123], v[160:163], v[168:171], 0
	v_mfma_f32_16x16x32_bf16 v[108:111], v[144:147], v[176:179], 0
	v_mfma_f32_16x16x32_bf16 v[104:107], v[160:163], v[176:179], 0
	v_mfma_f32_16x16x32_bf16 v[92:95], v[144:147], v[184:187], 0
	v_mfma_f32_16x16x32_bf16 v[88:91], v[160:163], v[184:187], 0
	v_mfma_f32_16x16x32_bf16 v[76:79], v[144:147], v[192:195], 0
	v_mfma_f32_16x16x32_bf16 v[72:75], v[160:163], v[192:195], 0
	v_mfma_f32_16x16x32_bf16 v[124:127], v[156:159], v[172:175], v[124:127]
	v_mfma_f32_16x16x32_bf16 v[120:123], v[164:167], v[172:175], v[120:123]
	v_mfma_f32_16x16x32_bf16 v[108:111], v[156:159], v[180:183], v[108:111]
	v_mfma_f32_16x16x32_bf16 v[104:107], v[164:167], v[180:183], v[104:107]
	v_mfma_f32_16x16x32_bf16 v[92:95], v[156:159], v[188:191], v[92:95]
	v_mfma_f32_16x16x32_bf16 v[88:91], v[164:167], v[188:191], v[88:91]
	v_mfma_f32_16x16x32_bf16 v[76:79], v[156:159], v[196:199], v[76:79]
	v_mfma_f32_16x16x32_bf16 v[72:75], v[164:167], v[196:199], v[72:75]
	s_barrier
	s_add_i32 s20, s51, s40
	s_add_u32 s80, s28, 0x80
	s_addc_u32 s81, s29, 0
	s_mov_b32 m0, s20
	ds_read_b128 v[200:203], v153
	ds_read_b128 v[204:207], v153 offset:1024
	ds_read_b128 v[208:211], v153 offset:2048
	ds_read_b128 v[212:215], v153 offset:3072
	global_load_lds_dwordx4 v130, s[28:29]
	s_add_i32 m0, s20, 0x2000
	s_nop 0
	global_load_lds_dwordx4 v134, s[28:29]
	s_cmp_lg_u32 s94, 0
	s_cbranch_scc1 .Lpw248_0a
	s_waitcnt vmcnt(10)
	s_branch .Lpw248_0b
.Lpw248_0a:
	s_waitcnt vmcnt(26)
.Lpw248_0b:
	s_barrier
	s_waitcnt lgkmcnt(0)
	s_waitcnt lgkmcnt(0)
	v_mfma_f32_16x16x32_bf16 v[116:119], v[200:203], v[168:171], 0
	v_mfma_f32_16x16x32_bf16 v[112:115], v[208:211], v[168:171], 0
	v_mfma_f32_16x16x32_bf16 v[100:103], v[200:203], v[176:179], 0
	v_mfma_f32_16x16x32_bf16 v[96:99], v[208:211], v[176:179], 0
	v_mfma_f32_16x16x32_bf16 v[84:87], v[200:203], v[184:187], 0
	v_mfma_f32_16x16x32_bf16 v[80:83], v[208:211], v[184:187], 0
	v_mfma_f32_16x16x32_bf16 v[68:71], v[200:203], v[192:195], 0
	v_mfma_f32_16x16x32_bf16 v[64:67], v[208:211], v[192:195], 0
	v_mfma_f32_16x16x32_bf16 v[116:119], v[204:207], v[172:175], v[116:119]
	v_mfma_f32_16x16x32_bf16 v[112:115], v[212:215], v[172:175], v[112:115]
	v_mfma_f32_16x16x32_bf16 v[100:103], v[204:207], v[180:183], v[100:103]
	v_mfma_f32_16x16x32_bf16 v[96:99], v[212:215], v[180:183], v[96:99]
	v_mfma_f32_16x16x32_bf16 v[84:87], v[204:207], v[188:191], v[84:87]
	v_mfma_f32_16x16x32_bf16 v[80:83], v[212:215], v[188:191], v[80:83]
	v_mfma_f32_16x16x32_bf16 v[68:71], v[204:207], v[196:199], v[68:71]
	v_mfma_f32_16x16x32_bf16 v[64:67], v[212:215], v[196:199], v[64:67]
	s_mov_b32 m0, s41
	s_add_u32 s82, s30, 0x80
	s_addc_u32 s83, s31, 0
	s_barrier
	ds_read_b128 v[168:171], v152 offset:16384
	ds_read_b128 v[172:175], v152 offset:17408
	ds_read_b128 v[176:179], v152 offset:18432
	ds_read_b128 v[180:183], v152 offset:19456
	ds_read_b128 v[184:187], v152 offset:20480
	ds_read_b128 v[188:191], v152 offset:21504
	ds_read_b128 v[192:195], v152 offset:22528
	ds_read_b128 v[196:199], v152 offset:23552
	global_load_lds_dwordx4 v128, s[30:31]
	s_mov_b32 m0, s42
	s_nop 0
	global_load_lds_dwordx4 v132, s[30:31]
	s_barrier
	s_waitcnt lgkmcnt(0)
	s_waitcnt lgkmcnt(0)
	v_mfma_f32_16x16x32_bf16 v[60:63], v[144:147], v[168:171], 0
	v_mfma_f32_16x16x32_bf16 v[56:59], v[160:163], v[168:171], 0
	v_mfma_f32_16x16x32_bf16 v[44:47], v[144:147], v[176:179], 0
	v_mfma_f32_16x16x32_bf16 v[40:43], v[160:163], v[176:179], 0
	v_mfma_f32_16x16x32_bf16 v[28:31], v[144:147], v[184:187], 0
	v_mfma_f32_16x16x32_bf16 v[24:27], v[160:163], v[184:187], 0
	v_mfma_f32_16x16x32_bf16 v[12:15], v[144:147], v[192:195], 0
	v_mfma_f32_16x16x32_bf16 v[8:11], v[160:163], v[192:195], 0
	v_mfma_f32_16x16x32_bf16 v[60:63], v[156:159], v[172:175], v[60:63]
	v_mfma_f32_16x16x32_bf16 v[56:59], v[164:167], v[172:175], v[56:59]
	v_mfma_f32_16x16x32_bf16 v[44:47], v[156:159], v[180:183], v[44:47]
	v_mfma_f32_16x16x32_bf16 v[40:43], v[164:167], v[180:183], v[40:43]
	v_mfma_f32_16x16x32_bf16 v[28:31], v[156:159], v[188:191], v[28:31]
	v_mfma_f32_16x16x32_bf16 v[24:27], v[164:167], v[188:191], v[24:27]
	v_mfma_f32_16x16x32_bf16 v[12:15], v[156:159], v[196:199], v[12:15]
	v_mfma_f32_16x16x32_bf16 v[8:11], v[164:167], v[196:199], v[8:11]
	s_barrier
	s_add_u32 s20, s28, 0xb0000
	s_addc_u32 s21, s29, 0
	s_add_i32 s60, s52, s40
	s_mov_b32 m0, s60
	s_nop 0
	global_load_lds_dwordx4 v130, s[20:21]
	s_add_i32 m0, s60, 0x2000
	s_nop 0
	global_load_lds_dwordx4 v134, s[20:21]
	s_cmp_lg_u32 s94, 0
	s_cbranch_scc1 .Lpw248_1a
	s_waitcnt vmcnt(8)
	s_branch .Lpw248_1b
.Lpw248_1a:
	s_waitcnt vmcnt(24)
.Lpw248_1b:
	s_barrier
	v_mfma_f32_16x16x32_bf16 v[52:55], v[200:203], v[168:171], 0
	v_mfma_f32_16x16x32_bf16 v[48:51], v[208:211], v[168:171], 0
	v_mfma_f32_16x16x32_bf16 v[36:39], v[200:203], v[176:179], 0
	v_mfma_f32_16x16x32_bf16 v[32:35], v[208:211], v[176:179], 0
	v_mfma_f32_16x16x32_bf16 v[20:23], v[200:203], v[184:187], 0
	v_mfma_f32_16x16x32_bf16 v[16:19], v[208:211], v[184:187], 0
	v_mfma_f32_16x16x32_bf16 v[4:7], v[200:203], v[192:195], 0
	v_mfma_f32_16x16x32_bf16 v[0:3], v[208:211], v[192:195], 0
	v_mfma_f32_16x16x32_bf16 v[52:55], v[204:207], v[172:175], v[52:55]
	v_mfma_f32_16x16x32_bf16 v[48:51], v[212:215], v[172:175], v[48:51]
	v_mfma_f32_16x16x32_bf16 v[36:39], v[204:207], v[180:183], v[36:39]
	v_mfma_f32_16x16x32_bf16 v[32:35], v[212:215], v[180:183], v[32:35]
	v_mfma_f32_16x16x32_bf16 v[20:23], v[204:207], v[188:191], v[20:23]
	v_mfma_f32_16x16x32_bf16 v[16:19], v[212:215], v[188:191], v[16:19]
	v_mfma_f32_16x16x32_bf16 v[4:7], v[204:207], v[196:199], v[4:7]
	v_mfma_f32_16x16x32_bf16 v[0:3], v[212:215], v[196:199], v[0:3]
	s_add_i32 s60, 0, 0x18000
	v_add_u32_e32 v155, s60, v149
	s_barrier
	s_branch .Lg248_mid

.Lg248_nox:
	s_mov_b32 s94, 1
	v_and_b32_e32 v156, 64, v154
	v_xor_b32_e32 v155, 16, v154
	v_add_u32_e32 v156, 64, v156
	v_xor_b32_e32 v157, 32, v154
	v_cmp_lt_i32_e32 vcc, v155, v156
	s_lshl_b32 s20, s12, 2
	s_ashr_i32 s21, s20, 31
	v_cndmask_b32_e32 v155, v154, v155, vcc
	v_cmp_lt_i32_e32 vcc, v157, v156
	v_lshlrev_b32_e32 v156, 2, v155
	s_waitcnt vmcnt(14)
	v_lshlrev_b32_e32 v168, 16, v158
	v_and_b32_e32 v169, 0xffff0000, v158
	v_lshlrev_b32_e32 v158, 16, v159
	v_and_b32_e32 v159, 0xffff0000, v159
	v_lshlrev_b32_e32 v172, 16, v162
	v_and_b32_e32 v173, 0xffff0000, v162
	v_lshlrev_b32_e32 v162, 16, v163
	v_and_b32_e32 v163, 0xffff0000, v163
	v_cndmask_b32_e32 v157, v154, v157, vcc
	v_lshlrev_b32_e32 v170, 16, v160
	v_and_b32_e32 v171, 0xffff0000, v160
	v_lshlrev_b32_e32 v160, 16, v161
	v_and_b32_e32 v161, 0xffff0000, v161
	v_lshlrev_b32_e32 v174, 16, v164
	v_and_b32_e32 v175, 0xffff0000, v164
	v_lshlrev_b32_e32 v164, 16, v165
	v_and_b32_e32 v165, 0xffff0000, v165
	v_pk_fma_f32 v[126:127], v[126:127], 0.5, v[158:159] op_sel_hi:[1,0,1]
	v_pk_fma_f32 v[124:125], v[124:125], 0.5, v[168:169] op_sel_hi:[1,0,1]
	v_pk_fma_f32 v[118:119], v[118:119], 0.5, v[162:163] op_sel_hi:[1,0,1]
	v_pk_fma_f32 v[116:117], v[116:117], 0.5, v[172:173] op_sel_hi:[1,0,1]
	v_lshlrev_b32_e32 v155, 2, v157
	v_pk_fma_f32 v[122:123], v[122:123], 0.5, v[160:161] op_sel_hi:[1,0,1]
	v_pk_fma_f32 v[120:121], v[120:121], 0.5, v[170:171] op_sel_hi:[1,0,1]
	v_pk_fma_f32 v[158:159], v[114:115], 0.5, v[164:165] op_sel_hi:[1,0,1]
	v_pk_fma_f32 v[160:161], v[112:113], 0.5, v[174:175] op_sel_hi:[1,0,1]
	v_mul_f32_e32 v114, v125, v125
	v_mul_f32_e32 v115, v127, v127
	v_mul_f32_e32 v157, v117, v117
	v_mul_f32_e32 v162, v119, v119
	v_cvt_pk_bf16_f32 v112, v124, v125
	v_mul_f32_e32 v125, v121, v121
	v_mul_f32_e32 v163, v161, v161
	v_fmac_f32_e32 v114, v124, v124
	v_fmac_f32_e32 v115, v126, v126
	v_fmac_f32_e32 v157, v116, v116
	v_fmac_f32_e32 v162, v118, v118
	v_cvt_pk_bf16_f32 v113, v126, v127
	v_mul_f32_e32 v127, v123, v123
	v_mul_f32_e32 v164, v159, v159
	v_fmac_f32_e32 v125, v120, v120
	v_fmac_f32_e32 v163, v160, v160
	v_add_f32_e32 v114, v114, v115
	v_add_f32_e32 v115, v157, v162
	v_fmac_f32_e32 v127, v122, v122
	v_fmac_f32_e32 v164, v158, v158
	v_add_f32_e32 v114, v125, v114
	v_add_f32_e32 v115, v163, v115
	v_add_f32_e32 v114, v127, v114
	v_add_f32_e32 v115, v164, v115
	v_add_f32_e32 v124, v114, v115
	ds_bpermute_b32 v125, v156, v124
	v_cvt_pk_bf16_f32 v114, v120, v121
	v_cvt_pk_bf16_f32 v115, v122, v123
	global_store_dwordx4 v[166:167], v[112:115], off
	s_waitcnt lgkmcnt(0)
	s_nop 0
	v_add_f32_e32 v112, v124, v125
	ds_bpermute_b32 v113, v155, v112
	v_cvt_pk_bf16_f32 v114, v116, v117
	v_cvt_pk_bf16_f32 v115, v118, v119
	v_cvt_pk_bf16_f32 v116, v160, v161
	v_cvt_pk_bf16_f32 v117, v158, v159
	global_store_dwordx4 v[166:167], v[114:117], off offset:256
	s_and_saveexec_b64 s[26:27], s[4:5]
	s_cbranch_execz .LBB0_251
	v_lshlrev_b64 v[114:115], 6, v[146:147]
	v_lshl_add_u64 v[114:115], s[16:17], 0, v[114:115]
	v_lshl_add_u64 v[114:115], s[20:21], 2, v[114:115]
	s_lshl_b32 s12, s45, 2
	v_lshl_add_u64 v[114:115], v[114:115], 0, s[12:13]
	s_waitcnt lgkmcnt(0)
	v_add_f32_e32 v112, v112, v113
	global_store_dword v[114:115], v112, off

.LBB0_353:
	s_mov_b64 s[10:11], 0x80
	s_and_b32 s4, s4, 3
	s_add_i32 m0, s37, 0x18000
	v_lshl_add_u64 v[6:7], v[6:7], 0, s[10:11]
	s_lshl_b32 s14, s5, 13
	s_lshl_b32 s18, s4, 5
	s_lshl_b32 s15, s4, 12
	s_waitcnt vmcnt(4)
	s_mov_b32 s94, 0
	s_barrier
	global_load_lds_dwordx4 v[6:7], off
	v_lshl_add_u64 v[4:5], v[4:5], 0, s[10:11]
	s_add_i32 m0, s37, 0x1a000
	s_add_i32 s55, s37, 0x8000
	s_add_i32 s56, s37, 0xa000
	global_load_lds_dwordx4 v[4:5], off
	v_lshl_add_u64 v[2:3], v[2:3], 0, s[10:11]
	s_mov_b32 m0, s55
	s_add_u32 s12, s38, 0x40080
	global_load_lds_dwordx4 v[2:3], off
	v_lshl_add_u64 v[0:1], v[0:1], 0, s[10:11]
	s_mov_b32 m0, s56
	s_addc_u32 s13, s39, 0
	global_load_lds_dwordx4 v[0:1], off
	s_add_i32 m0, s37, 0x1c000
	v_lshl_add_u64 v[0:1], s[12:13], 0, v[144:145]
	global_load_lds_dwordx4 v[0:1], off
	v_lshl_add_u64 v[0:1], s[12:13], 0, v[148:149]
	s_add_i32 m0, s37, 0x1e000
	v_mov_b32_e32 v159, v151
	global_load_lds_dwordx4 v[0:1], off
	v_and_b32_e32 v0, 15, v153
	v_lshl_or_b32 v178, s5, 6, v0
	v_lshrrev_b32_e32 v1, 1, v153
	s_lshl_b32 s5, s5, 8
	v_and_b32_e32 v152, 24, v1
	s_add_i32 s5, s5, 0
	v_lshlrev_b32_e32 v1, 1, v152
	s_add_i32 s5, s5, 0x20000
	v_lshl_or_b32 v1, v0, 6, v1
	v_lshlrev_b32_e32 v0, 2, v0
	s_add_u32 s12, s26, 0xf800000
	v_and_b32_e32 v2, 32, v0
	s_addc_u32 s13, s27, 0
	v_bitop3_b32 v3, v1, s14, v2 bitop3:0xde
	s_add_u32 s14, s26, 0xe000000
	v_bitop3_b32 v179, s15, v1, v2 bitop3:0xf6
	s_addc_u32 s15, s27, 0
	s_cmp_lt_u32 s4, 2
	s_cselect_b64 s[16:17], -1, 0
	s_lshl_b32 s57, s4, 6
	s_lshl_b32 s4, s4, 7
	s_add_u32 s4, s26, s4
	v_add_u32_e32 v180, s5, v0
	s_addc_u32 s5, s27, 0
	s_add_u32 s19, s4, 0xd3fff00
	s_addc_u32 s20, s5, 0
	s_add_u32 s21, s4, 0xc800000
	v_lshlrev_b32_e32 v150, 2, v152
	s_addc_u32 s30, s5, 0
	v_lshl_add_u64 v[0:1], s[26:27], 0, v[150:151]
	s_mov_b64 s[4:5], 0x2800000
	v_lshl_add_u64 v[154:155], v[0:1], 0, s[4:5]
	s_mov_b64 s[4:5], 0x2900000
	v_lshl_add_u64 v[156:157], v[0:1], 0, s[4:5]
	v_lshlrev_b32_e32 v0, 14, v8
	v_and_b32_e32 v0, 0xffff8000, v0
	v_lshl_add_u32 v0, v9, 11, v0
	v_and_b32_e32 v1, 1, v8
	v_lshl_or_b32 v0, v1, 6, v0
	s_add_u32 s58, s26, 0x9800000
	v_lshl_add_u32 v158, v10, 1, v0
	v_lshlrev_b32_e32 v0, 14, v11
	s_addc_u32 s59, s27, 0
	v_and_b32_e32 v0, 0xffff8000, v0
	s_waitcnt vmcnt(6)
	s_and_b64 s[4:5], s[16:17], exec
	v_lshl_add_u32 v0, v12, 11, v0
	v_and_b32_e32 v1, 1, v11
	s_cselect_b32 s60, s30, s20
	s_cselect_b32 s61, s21, s19
	v_lshl_or_b32 v0, v1, 6, v0
	s_add_i32 s63, 0, 0x10000
	s_add_i32 s64, 0, 0x14000
	v_lshl_add_u32 v160, v13, 1, v0
	v_mov_b32_e32 v161, v151
	v_mov_b64_e32 v[162:163], 0x6c0
	v_mov_b64_e32 v[164:165], 0x6bf
	s_movk_i32 s62, 0xd9
	v_add_u32_e32 v181, s63, v179
	v_add_u32_e32 v182, 0, v3
	v_add_u32_e32 v183, s64, v179
	s_lshl_b32 s65, s18, 1
	s_movk_i32 s66, 0x3f80
	s_movk_i32 s67, 0x3f70
	s_movk_i32 s68, 0x3f60
	s_movk_i32 s69, 0x3f50
	v_mov_b32_e32 v184, 0x1fcf
	v_mov_b32_e32 v185, 0x7cf
	v_mov_b32_e32 v186, 0x1fdf
	v_mov_b32_e32 v187, 0x7df
	v_mov_b32_e32 v188, 0x1fef
	v_mov_b32_e32 v189, 0x7ef
	v_mov_b32_e32 v190, 0x1fff
	v_mov_b32_e32 v191, 0x7ff
	s_barrier
	s_branch .LBB0_356

.Lg359_noy:
	ds_read_b128 v[128:131], v181
	ds_read_b128 v[132:135], v181 offset:1024
	ds_read_b128 v[136:139], v181 offset:2048
	ds_read_b128 v[166:169], v181 offset:3072
	s_add_u32 s38, s8, 0xfffc0080
	s_addc_u32 s39, s9, -1
	s_cmp_eq_u32 s75, 12
	s_cselect_b32 s41, s21, s39
	s_cselect_b32 s40, s71, s38
	s_cselect_b32 s39, s19, s74
	s_cselect_b32 s38, s72, s73
	s_add_i32 m0, s37, 0xc000
	ds_read_b128 v[170:173], v182
	ds_read_b128 v[174:177], v182 offset:1024
	ds_read_b128 v[192:195], v182 offset:2048
	ds_read_b128 v[196:199], v182 offset:3072
	ds_read_b128 v[200:203], v182 offset:4096
	ds_read_b128 v[204:207], v182 offset:5120
	ds_read_b128 v[208:211], v182 offset:6144
	ds_read_b128 v[212:215], v182 offset:7168
	global_load_lds_dwordx4 v158, s[8:9]
	s_add_i32 m0, s37, 0xe000
	s_nop 0
	global_load_lds_dwordx4 v160, s[8:9]
	s_waitcnt lgkmcnt(8)
	s_barrier
	s_waitcnt lgkmcnt(0)
	s_waitcnt lgkmcnt(0)
	v_mfma_f32_16x16x32_bf16 v[124:127], v[128:131], v[170:173], 0
	v_mfma_f32_16x16x32_bf16 v[116:119], v[136:139], v[170:173], 0
	v_mfma_f32_16x16x32_bf16 v[108:111], v[128:131], v[192:195], 0
	v_mfma_f32_16x16x32_bf16 v[100:103], v[136:139], v[192:195], 0
	v_mfma_f32_16x16x32_bf16 v[92:95], v[128:131], v[200:203], 0
	v_mfma_f32_16x16x32_bf16 v[84:87], v[136:139], v[200:203], 0
	v_mfma_f32_16x16x32_bf16 v[76:79], v[128:131], v[208:211], 0
	v_mfma_f32_16x16x32_bf16 v[68:71], v[136:139], v[208:211], 0
	v_mfma_f32_16x16x32_bf16 v[124:127], v[132:135], v[174:177], v[124:127]
	v_mfma_f32_16x16x32_bf16 v[116:119], v[166:169], v[174:177], v[116:119]
	v_mfma_f32_16x16x32_bf16 v[108:111], v[132:135], v[196:199], v[108:111]
	v_mfma_f32_16x16x32_bf16 v[100:103], v[166:169], v[196:199], v[100:103]
	v_mfma_f32_16x16x32_bf16 v[92:95], v[132:135], v[204:207], v[92:95]
	v_mfma_f32_16x16x32_bf16 v[84:87], v[166:169], v[204:207], v[84:87]
	v_mfma_f32_16x16x32_bf16 v[76:79], v[132:135], v[212:215], v[76:79]
	v_mfma_f32_16x16x32_bf16 v[68:71], v[166:169], v[212:215], v[68:71]
	s_barrier
	s_add_i32 s76, s63, s46
	s_add_u32 s80, s38, 0x80
	s_addc_u32 s81, s39, 0
	s_mov_b32 m0, s76
	ds_read_b128 v[216:219], v183
	ds_read_b128 v[220:223], v183 offset:1024
	ds_read_b128 v[224:227], v183 offset:2048
	ds_read_b128 v[228:231], v183 offset:3072
	global_load_lds_dwordx4 v144, s[38:39]
	s_add_i32 m0, s76, 0x2000
	s_nop 0
	global_load_lds_dwordx4 v148, s[38:39]
	s_cmp_lg_u32 s94, 0
	s_cbranch_scc1 .Lpw359_0a
	s_waitcnt vmcnt(10)
	s_branch .Lpw359_0b

.Lpw359_0b:
	s_barrier
	s_waitcnt lgkmcnt(0)
	s_waitcnt lgkmcnt(0)
	v_mfma_f32_16x16x32_bf16 v[120:123], v[216:219], v[170:173], 0
	v_mfma_f32_16x16x32_bf16 v[112:115], v[224:227], v[170:173], 0
	v_mfma_f32_16x16x32_bf16 v[104:107], v[216:219], v[192:195], 0
	v_mfma_f32_16x16x32_bf16 v[96:99], v[224:227], v[192:195], 0
	v_mfma_f32_16x16x32_bf16 v[88:91], v[216:219], v[200:203], 0
	v_mfma_f32_16x16x32_bf16 v[80:83], v[224:227], v[200:203], 0
	v_mfma_f32_16x16x32_bf16 v[72:75], v[216:219], v[208:211], 0
	v_mfma_f32_16x16x32_bf16 v[64:67], v[224:227], v[208:211], 0
	v_mfma_f32_16x16x32_bf16 v[120:123], v[220:223], v[174:177], v[120:123]
	v_mfma_f32_16x16x32_bf16 v[112:115], v[228:231], v[174:177], v[112:115]
	v_mfma_f32_16x16x32_bf16 v[104:107], v[220:223], v[196:199], v[104:107]
	v_mfma_f32_16x16x32_bf16 v[96:99], v[228:231], v[196:199], v[96:99]
	v_mfma_f32_16x16x32_bf16 v[88:91], v[220:223], v[204:207], v[88:91]
	v_mfma_f32_16x16x32_bf16 v[80:83], v[228:231], v[204:207], v[80:83]
	v_mfma_f32_16x16x32_bf16 v[72:75], v[220:223], v[212:215], v[72:75]
	v_mfma_f32_16x16x32_bf16 v[64:67], v[228:231], v[212:215], v[64:67]
	s_mov_b32 m0, s37
	s_add_u32 s82, s40, 0x80
	s_addc_u32 s83, s41, 0
	s_barrier
	ds_read_b128 v[170:173], v182 offset:16384
	ds_read_b128 v[174:177], v182 offset:17408
	ds_read_b128 v[192:195], v182 offset:18432
	ds_read_b128 v[196:199], v182 offset:19456
	ds_read_b128 v[200:203], v182 offset:20480
	ds_read_b128 v[204:207], v182 offset:21504
	ds_read_b128 v[208:211], v182 offset:22528
	ds_read_b128 v[212:215], v182 offset:23552
	global_load_lds_dwordx4 v142, s[40:41]
	s_mov_b32 m0, s51
	s_nop 0
	global_load_lds_dwordx4 v146, s[40:41]
	s_barrier
	s_waitcnt lgkmcnt(0)
	s_waitcnt lgkmcnt(0)
	v_mfma_f32_16x16x32_bf16 v[60:63], v[128:131], v[170:173], 0
	v_mfma_f32_16x16x32_bf16 v[52:55], v[136:139], v[170:173], 0
	v_mfma_f32_16x16x32_bf16 v[44:47], v[128:131], v[192:195], 0
	v_mfma_f32_16x16x32_bf16 v[36:39], v[136:139], v[192:195], 0
	v_mfma_f32_16x16x32_bf16 v[28:31], v[128:131], v[200:203], 0
	v_mfma_f32_16x16x32_bf16 v[20:23], v[136:139], v[200:203], 0
	v_mfma_f32_16x16x32_bf16 v[12:15], v[128:131], v[208:211], 0
	v_mfma_f32_16x16x32_bf16 v[4:7], v[136:139], v[208:211], 0
	v_mfma_f32_16x16x32_bf16 v[60:63], v[132:135], v[174:177], v[60:63]
	v_mfma_f32_16x16x32_bf16 v[52:55], v[166:169], v[174:177], v[52:55]
	v_mfma_f32_16x16x32_bf16 v[44:47], v[132:135], v[196:199], v[44:47]
	v_mfma_f32_16x16x32_bf16 v[36:39], v[166:169], v[196:199], v[36:39]
	v_mfma_f32_16x16x32_bf16 v[28:31], v[132:135], v[204:207], v[28:31]
	v_mfma_f32_16x16x32_bf16 v[20:23], v[166:169], v[204:207], v[20:23]
	v_mfma_f32_16x16x32_bf16 v[12:15], v[132:135], v[212:215], v[12:15]
	v_mfma_f32_16x16x32_bf16 v[4:7], v[166:169], v[212:215], v[4:7]
	s_barrier
	s_add_u32 s76, s38, 0x40000
	s_addc_u32 s77, s39, 0
	s_add_i32 s78, s64, s46
	s_mov_b32 m0, s78
	s_nop 0
	global_load_lds_dwordx4 v144, s[76:77]
	s_add_i32 m0, s78, 0x2000
	s_nop 0
	global_load_lds_dwordx4 v148, s[76:77]
	s_cmp_lg_u32 s94, 0
	s_cbranch_scc1 .Lpw359_1a
	s_waitcnt vmcnt(8)
	s_branch .Lpw359_1b

.Lpw359_1b:
	s_barrier
	v_mfma_f32_16x16x32_bf16 v[56:59], v[216:219], v[170:173], 0
	v_mfma_f32_16x16x32_bf16 v[48:51], v[224:227], v[170:173], 0
	v_mfma_f32_16x16x32_bf16 v[40:43], v[216:219], v[192:195], 0
	v_mfma_f32_16x16x32_bf16 v[32:35], v[224:227], v[192:195], 0
	v_mfma_f32_16x16x32_bf16 v[24:27], v[216:219], v[200:203], 0
	v_mfma_f32_16x16x32_bf16 v[16:19], v[224:227], v[200:203], 0
	v_mfma_f32_16x16x32_bf16 v[8:11], v[216:219], v[208:211], 0
	v_mfma_f32_16x16x32_bf16 v[0:3], v[224:227], v[208:211], 0
	v_mfma_f32_16x16x32_bf16 v[56:59], v[220:223], v[174:177], v[56:59]
	v_mfma_f32_16x16x32_bf16 v[48:51], v[228:231], v[174:177], v[48:51]
	v_mfma_f32_16x16x32_bf16 v[40:43], v[220:223], v[196:199], v[40:43]
	v_mfma_f32_16x16x32_bf16 v[32:35], v[228:231], v[196:199], v[32:35]
	v_mfma_f32_16x16x32_bf16 v[24:27], v[220:223], v[204:207], v[24:27]
	v_mfma_f32_16x16x32_bf16 v[16:19], v[228:231], v[204:207], v[16:19]
	v_mfma_f32_16x16x32_bf16 v[8:11], v[220:223], v[212:215], v[8:11]
	v_mfma_f32_16x16x32_bf16 v[0:3], v[228:231], v[212:215], v[0:3]
	s_add_i32 s76, 0, 0x18000
	v_add_u32_e32 v150, s76, v179
	s_barrier
	s_branch .Lg359_mid

.Lg359_nox:
	s_mov_b32 s94, 1
	s_lshl_b32 s19, s7, 10
	v_lshl_add_u32 v166, s6, 8, v178
	s_cmp_gt_i32 s36, 2
	s_mov_b64 s[6:7], -1
	s_cbranch_scc0 .LBB0_373
	s_cmp_gt_u32 s36, 8
	s_cbranch_scc1 .LBB0_372
	s_cmp_lt_i32 s36, 4
	s_cbranch_scc1 .LBB0_406
	s_cmp_lg_u32 s36, 4
	s_mov_b64 s[8:9], -1
	s_cbranch_scc0 .LBB0_369
	s_lshl_b32 s6, s36, 9
	s_add_u32 s21, s26, s6
	s_addc_u32 s38, s27, 0
	s_cmp_gt_u32 s36, 6
	s_cbranch_scc0 .LBB0_366
	s_add_u32 s6, s21, 0x13fff200
	s_addc_u32 s7, s38, 0
	s_mov_b64 s[8:9], 0

.LBB0_781:
	s_add_u32 s10, s6, 0x3800000
	s_addc_u32 s11, s7, 0
	s_add_u32 s12, s6, 0x3000000
	s_addc_u32 s13, s7, 0
	s_and_b32 s49, s14, 3
	s_mov_b64 s[14:15], 0x80
	s_add_i32 m0, s45, 0x18000
	v_lshl_add_u64 v[6:7], v[6:7], 0, s[14:15]
	s_lshl_b32 s16, s5, 13
	s_lshl_b32 s17, s49, 12
	s_waitcnt vmcnt(4)
	s_mov_b32 s94, 0
	s_barrier
	global_load_lds_dwordx4 v[6:7], off
	v_lshl_add_u64 v[4:5], v[4:5], 0, s[14:15]
	s_add_i32 m0, s45, 0x1a000
	s_add_i32 s50, s45, 0x8000
	s_add_i32 s51, s45, 0xa000
	global_load_lds_dwordx4 v[4:5], off
	v_lshl_add_u64 v[2:3], v[2:3], 0, s[14:15]
	s_mov_b32 m0, s50
	s_add_u32 s6, s30, 0x40080
	global_load_lds_dwordx4 v[2:3], off
	v_lshl_add_u64 v[0:1], v[0:1], 0, s[14:15]
	s_mov_b32 m0, s51
	s_addc_u32 s7, s31, 0
	global_load_lds_dwordx4 v[0:1], off
	s_add_i32 m0, s45, 0x1c000
	v_lshl_add_u64 v[0:1], s[6:7], 0, v[132:133]
	global_load_lds_dwordx4 v[0:1], off
	v_lshl_add_u64 v[0:1], s[6:7], 0, v[128:129]
	s_add_i32 m0, s45, 0x1e000
	s_sext_i32_i8 s56, s4
	global_load_lds_dwordx4 v[0:1], off
	v_bfe_u32 v0, v8, 4, 2
	v_and_b32_e32 v1, 15, v8
	v_lshlrev_b32_e32 v3, 4, v0
	v_lshl_or_b32 v148, s5, 6, v1
	v_lshlrev_b32_e32 v2, 3, v0
	v_lshl_or_b32 v1, v1, 6, v3
	v_lshlrev_b32_e32 v3, 2, v8
	v_cmp_eq_u32_e64 s[4:5], 0, v0
	v_lshlrev_b32_e32 v0, 14, v13
	v_and_b32_e32 v3, 32, v3
	v_and_b32_e32 v0, 0xffff8000, v0
	v_bitop3_b32 v4, v1, s16, v3 bitop3:0xde
	v_bitop3_b32 v149, s17, v1, v3 bitop3:0xf6
	v_lshl_add_u32 v0, v12, 11, v0
	v_and_b32_e32 v1, 1, v13
	v_lshl_or_b32 v0, v1, 6, v0
	v_lshl_add_u32 v136, v14, 1, v0
	v_lshlrev_b32_e32 v0, 14, v9
	v_and_b32_e32 v0, 0xffff8000, v0
	s_waitcnt vmcnt(6)
	v_lshl_add_u32 v0, v10, 11, v0
	v_and_b32_e32 v1, 1, v9
	v_lshl_or_b32 v0, v1, 6, v0
	s_add_i32 s53, 0, 0x10000
	s_add_i32 s54, 0, 0x14000
	v_lshl_or_b32 v150, s49, 5, v2
	s_ashr_i32 s52, s36, 31
	v_mov_b32_e32 v137, v133
	v_lshl_add_u32 v138, v11, 1, v0
	v_mov_b32_e32 v139, v133
	v_mov_b64_e32 v[140:141], 0x300
	v_mov_b64_e32 v[142:143], 0x2ff
	v_add_u32_e32 v151, s53, v149
	v_add_u32_e32 v152, 0, v4
	v_add_u32_e32 v153, s54, v149
	v_mbcnt_hi_u32_b32 v154, -1, v241
	s_mov_b32 s55, 0
	s_barrier
	s_branch .LBB0_783

.Lg786_noy:
	ds_read_b128 v[144:147], v151
	ds_read_b128 v[156:159], v151 offset:1024
	ds_read_b128 v[160:163], v151 offset:2048
	ds_read_b128 v[164:167], v151 offset:3072
	s_add_u32 s30, s28, 0xfffc0080
	s_addc_u32 s31, s29, -1
	s_cmp_eq_u32 s61, 12
	s_cselect_b32 s35, s19, s31
	s_cselect_b32 s34, s57, s30
	s_cselect_b32 s31, s17, s60
	s_cselect_b32 s30, s58, s59
	s_add_i32 m0, s45, 0xc000
	ds_read_b128 v[168:171], v152
	ds_read_b128 v[172:175], v152 offset:1024
	ds_read_b128 v[176:179], v152 offset:2048
	ds_read_b128 v[180:183], v152 offset:3072
	ds_read_b128 v[184:187], v152 offset:4096
	ds_read_b128 v[188:191], v152 offset:5120
	ds_read_b128 v[192:195], v152 offset:6144
	ds_read_b128 v[196:199], v152 offset:7168
	global_load_lds_dwordx4 v136, s[28:29]
	s_add_i32 m0, s45, 0xe000
	s_nop 0
	global_load_lds_dwordx4 v138, s[28:29]
	s_waitcnt lgkmcnt(8)
	s_barrier
	s_waitcnt lgkmcnt(0)
	s_waitcnt lgkmcnt(0)
	v_mfma_f32_16x16x32_bf16 v[124:127], v[144:147], v[168:171], 0
	v_mfma_f32_16x16x32_bf16 v[120:123], v[160:163], v[168:171], 0
	v_mfma_f32_16x16x32_bf16 v[108:111], v[144:147], v[176:179], 0
	v_mfma_f32_16x16x32_bf16 v[104:107], v[160:163], v[176:179], 0
	v_mfma_f32_16x16x32_bf16 v[92:95], v[144:147], v[184:187], 0
	v_mfma_f32_16x16x32_bf16 v[88:91], v[160:163], v[184:187], 0
	v_mfma_f32_16x16x32_bf16 v[76:79], v[144:147], v[192:195], 0
	v_mfma_f32_16x16x32_bf16 v[72:75], v[160:163], v[192:195], 0
	v_mfma_f32_16x16x32_bf16 v[124:127], v[156:159], v[172:175], v[124:127]
	v_mfma_f32_16x16x32_bf16 v[120:123], v[164:167], v[172:175], v[120:123]
	v_mfma_f32_16x16x32_bf16 v[108:111], v[156:159], v[180:183], v[108:111]
	v_mfma_f32_16x16x32_bf16 v[104:107], v[164:167], v[180:183], v[104:107]
	v_mfma_f32_16x16x32_bf16 v[92:95], v[156:159], v[188:191], v[92:95]
	v_mfma_f32_16x16x32_bf16 v[88:91], v[164:167], v[188:191], v[88:91]
	v_mfma_f32_16x16x32_bf16 v[76:79], v[156:159], v[196:199], v[76:79]
	v_mfma_f32_16x16x32_bf16 v[72:75], v[164:167], v[196:199], v[72:75]
	s_barrier
	s_add_i32 s62, s53, s42
	s_add_u32 s80, s30, 0x80
	s_addc_u32 s81, s31, 0
	s_mov_b32 m0, s62
	ds_read_b128 v[200:203], v153
	ds_read_b128 v[204:207], v153 offset:1024
	ds_read_b128 v[208:211], v153 offset:2048
	ds_read_b128 v[212:215], v153 offset:3072
	global_load_lds_dwordx4 v132, s[30:31]
	s_add_i32 m0, s62, 0x2000
	s_nop 0
	global_load_lds_dwordx4 v128, s[30:31]
	s_cmp_lg_u32 s94, 0
	s_cbranch_scc1 .Lpw786_0a
	s_waitcnt vmcnt(10)
	s_branch .Lpw786_0b

.Lpw786_0b:
	s_barrier
	s_waitcnt lgkmcnt(0)
	s_waitcnt lgkmcnt(0)
	v_mfma_f32_16x16x32_bf16 v[116:119], v[200:203], v[168:171], 0
	v_mfma_f32_16x16x32_bf16 v[112:115], v[208:211], v[168:171], 0
	v_mfma_f32_16x16x32_bf16 v[100:103], v[200:203], v[176:179], 0
	v_mfma_f32_16x16x32_bf16 v[96:99], v[208:211], v[176:179], 0
	v_mfma_f32_16x16x32_bf16 v[84:87], v[200:203], v[184:187], 0
	v_mfma_f32_16x16x32_bf16 v[80:83], v[208:211], v[184:187], 0
	v_mfma_f32_16x16x32_bf16 v[68:71], v[200:203], v[192:195], 0
	v_mfma_f32_16x16x32_bf16 v[64:67], v[208:211], v[192:195], 0
	v_mfma_f32_16x16x32_bf16 v[116:119], v[204:207], v[172:175], v[116:119]
	v_mfma_f32_16x16x32_bf16 v[112:115], v[212:215], v[172:175], v[112:115]
	v_mfma_f32_16x16x32_bf16 v[100:103], v[204:207], v[180:183], v[100:103]
	v_mfma_f32_16x16x32_bf16 v[96:99], v[212:215], v[180:183], v[96:99]
	v_mfma_f32_16x16x32_bf16 v[84:87], v[204:207], v[188:191], v[84:87]
	v_mfma_f32_16x16x32_bf16 v[80:83], v[212:215], v[188:191], v[80:83]
	v_mfma_f32_16x16x32_bf16 v[68:71], v[204:207], v[196:199], v[68:71]
	v_mfma_f32_16x16x32_bf16 v[64:67], v[212:215], v[196:199], v[64:67]
	s_mov_b32 m0, s45
	s_add_u32 s82, s34, 0x80
	s_addc_u32 s83, s35, 0
	s_barrier
	ds_read_b128 v[168:171], v152 offset:16384
	ds_read_b128 v[172:175], v152 offset:17408
	ds_read_b128 v[176:179], v152 offset:18432
	ds_read_b128 v[180:183], v152 offset:19456
	ds_read_b128 v[184:187], v152 offset:20480
	ds_read_b128 v[188:191], v152 offset:21504
	ds_read_b128 v[192:195], v152 offset:22528
	ds_read_b128 v[196:199], v152 offset:23552
	global_load_lds_dwordx4 v134, s[34:35]
	s_mov_b32 m0, s46
	s_nop 0
	global_load_lds_dwordx4 v130, s[34:35]
	s_barrier
	s_waitcnt lgkmcnt(0)
	s_waitcnt lgkmcnt(0)
	v_mfma_f32_16x16x32_bf16 v[60:63], v[144:147], v[168:171], 0
	v_mfma_f32_16x16x32_bf16 v[56:59], v[160:163], v[168:171], 0
	v_mfma_f32_16x16x32_bf16 v[44:47], v[144:147], v[176:179], 0
	v_mfma_f32_16x16x32_bf16 v[40:43], v[160:163], v[176:179], 0
	v_mfma_f32_16x16x32_bf16 v[28:31], v[144:147], v[184:187], 0
	v_mfma_f32_16x16x32_bf16 v[24:27], v[160:163], v[184:187], 0
	v_mfma_f32_16x16x32_bf16 v[12:15], v[144:147], v[192:195], 0
	v_mfma_f32_16x16x32_bf16 v[8:11], v[160:163], v[192:195], 0
	v_mfma_f32_16x16x32_bf16 v[60:63], v[156:159], v[172:175], v[60:63]
	v_mfma_f32_16x16x32_bf16 v[56:59], v[164:167], v[172:175], v[56:59]
	v_mfma_f32_16x16x32_bf16 v[44:47], v[156:159], v[180:183], v[44:47]
	v_mfma_f32_16x16x32_bf16 v[40:43], v[164:167], v[180:183], v[40:43]
	v_mfma_f32_16x16x32_bf16 v[28:31], v[156:159], v[188:191], v[28:31]
	v_mfma_f32_16x16x32_bf16 v[24:27], v[164:167], v[188:191], v[24:27]
	v_mfma_f32_16x16x32_bf16 v[12:15], v[156:159], v[196:199], v[12:15]
	v_mfma_f32_16x16x32_bf16 v[8:11], v[164:167], v[196:199], v[8:11]
	s_barrier
	s_add_u32 s62, s30, 0x40000
	s_addc_u32 s63, s31, 0
	s_add_i32 s64, s54, s42
	s_mov_b32 m0, s64
	s_nop 0
	global_load_lds_dwordx4 v132, s[62:63]
	s_add_i32 m0, s64, 0x2000
	s_nop 0
	global_load_lds_dwordx4 v128, s[62:63]
	s_cmp_lg_u32 s94, 0
	s_cbranch_scc1 .Lpw786_1a
	s_waitcnt vmcnt(8)
	s_branch .Lpw786_1b

.Lpw786_1b:
	s_barrier
	v_mfma_f32_16x16x32_bf16 v[52:55], v[200:203], v[168:171], 0
	v_mfma_f32_16x16x32_bf16 v[48:51], v[208:211], v[168:171], 0
	v_mfma_f32_16x16x32_bf16 v[36:39], v[200:203], v[176:179], 0
	v_mfma_f32_16x16x32_bf16 v[32:35], v[208:211], v[176:179], 0
	v_mfma_f32_16x16x32_bf16 v[20:23], v[200:203], v[184:187], 0
	v_mfma_f32_16x16x32_bf16 v[16:19], v[208:211], v[184:187], 0
	v_mfma_f32_16x16x32_bf16 v[4:7], v[200:203], v[192:195], 0
	v_mfma_f32_16x16x32_bf16 v[0:3], v[208:211], v[192:195], 0
	v_mfma_f32_16x16x32_bf16 v[52:55], v[204:207], v[172:175], v[52:55]
	v_mfma_f32_16x16x32_bf16 v[48:51], v[212:215], v[172:175], v[48:51]
	v_mfma_f32_16x16x32_bf16 v[36:39], v[204:207], v[180:183], v[36:39]
	v_mfma_f32_16x16x32_bf16 v[32:35], v[212:215], v[180:183], v[32:35]
	v_mfma_f32_16x16x32_bf16 v[20:23], v[204:207], v[188:191], v[20:23]
	v_mfma_f32_16x16x32_bf16 v[16:19], v[212:215], v[188:191], v[16:19]
	v_mfma_f32_16x16x32_bf16 v[4:7], v[204:207], v[196:199], v[4:7]
	v_mfma_f32_16x16x32_bf16 v[0:3], v[212:215], v[196:199], v[0:3]
	s_add_i32 s62, 0, 0x18000
	v_add_u32_e32 v155, s62, v149
	s_barrier
	s_branch .Lg786_mid

.Lg786_nox:
	s_mov_b32 s94, 1
	v_and_b32_e32 v156, 64, v154
	v_xor_b32_e32 v155, 16, v154
	v_add_u32_e32 v156, 64, v156
	v_xor_b32_e32 v157, 32, v154
	v_cmp_lt_i32_e32 vcc, v155, v156
	s_lshl_b32 s28, s56, 2
	s_ashr_i32 s29, s28, 31
	v_cndmask_b32_e32 v155, v154, v155, vcc
	v_cmp_lt_i32_e32 vcc, v157, v156
	v_lshlrev_b32_e32 v156, 2, v155
	s_waitcnt vmcnt(14)
	v_lshlrev_b32_e32 v168, 16, v158
	v_and_b32_e32 v169, 0xffff0000, v158
	v_lshlrev_b32_e32 v158, 16, v159
	v_and_b32_e32 v159, 0xffff0000, v159
	v_lshlrev_b32_e32 v172, 16, v162
	v_and_b32_e32 v173, 0xffff0000, v162
	v_lshlrev_b32_e32 v162, 16, v163
	v_and_b32_e32 v163, 0xffff0000, v163
	v_cndmask_b32_e32 v157, v154, v157, vcc
	v_lshlrev_b32_e32 v170, 16, v160
	v_and_b32_e32 v171, 0xffff0000, v160
	v_lshlrev_b32_e32 v160, 16, v161
	v_and_b32_e32 v161, 0xffff0000, v161
	v_lshlrev_b32_e32 v174, 16, v164
	v_and_b32_e32 v175, 0xffff0000, v164
	v_lshlrev_b32_e32 v164, 16, v165
	v_and_b32_e32 v165, 0xffff0000, v165
	v_pk_add_f32 v[126:127], v[126:127], v[158:159]
	v_pk_add_f32 v[124:125], v[124:125], v[168:169]
	v_pk_add_f32 v[118:119], v[118:119], v[162:163]
	v_pk_add_f32 v[116:117], v[116:117], v[172:173]
	v_lshlrev_b32_e32 v155, 2, v157
	v_pk_add_f32 v[122:123], v[122:123], v[160:161]
	v_pk_add_f32 v[120:121], v[120:121], v[170:171]
	v_pk_add_f32 v[158:159], v[114:115], v[164:165]
	v_pk_add_f32 v[160:161], v[112:113], v[174:175]
	v_mul_f32_e32 v114, v125, v125
	v_mul_f32_e32 v115, v127, v127
	v_mul_f32_e32 v157, v117, v117
	v_mul_f32_e32 v162, v119, v119
	v_cvt_pk_bf16_f32 v112, v124, v125
	v_mul_f32_e32 v125, v121, v121
	v_mul_f32_e32 v163, v161, v161
	v_fmac_f32_e32 v114, v124, v124
	v_fmac_f32_e32 v115, v126, v126
	v_fmac_f32_e32 v157, v116, v116
	v_fmac_f32_e32 v162, v118, v118
	v_cvt_pk_bf16_f32 v113, v126, v127
	v_mul_f32_e32 v127, v123, v123
	v_mul_f32_e32 v164, v159, v159
	v_fmac_f32_e32 v125, v120, v120
	v_fmac_f32_e32 v163, v160, v160
	v_add_f32_e32 v114, v114, v115
	v_add_f32_e32 v115, v157, v162
	v_fmac_f32_e32 v127, v122, v122
	v_fmac_f32_e32 v164, v158, v158
	v_add_f32_e32 v114, v125, v114
	v_add_f32_e32 v115, v163, v115
	v_add_f32_e32 v114, v127, v114
	v_add_f32_e32 v115, v164, v115
	v_add_f32_e32 v124, v114, v115
	ds_bpermute_b32 v125, v156, v124
	v_cvt_pk_bf16_f32 v114, v120, v121
	v_cvt_pk_bf16_f32 v115, v122, v123
	global_store_dwordx4 v[166:167], v[112:115], off
	s_waitcnt lgkmcnt(0)
	s_nop 0
	v_add_f32_e32 v112, v124, v125
	ds_bpermute_b32 v113, v155, v112
	v_cvt_pk_bf16_f32 v114, v116, v117
	v_cvt_pk_bf16_f32 v115, v118, v119
	v_cvt_pk_bf16_f32 v116, v160, v161
	v_cvt_pk_bf16_f32 v117, v158, v159
	global_store_dwordx4 v[166:167], v[114:117], off offset:256
	s_and_saveexec_b64 s[30:31], s[4:5]
	s_cbranch_execz .LBB0_789
	v_lshlrev_b64 v[114:115], 6, v[146:147]
	v_lshl_add_u64 v[114:115], s[12:13], 0, v[114:115]
	v_lshl_add_u64 v[114:115], s[28:29], 2, v[114:115]
	s_lshl_b32 s8, s49, 2
	v_lshl_add_u64 v[114:115], v[114:115], 0, s[8:9]
	s_waitcnt lgkmcnt(0)
	v_add_f32_e32 v112, v112, v113
	global_store_dword v[114:115], v112, off

.LBB0_889:
	s_lshl_b32 s6, s6, 5
	s_and_b32 s13, s6, 0x60
	s_lshl_b32 s12, s5, 13
	s_lshl_b32 s14, s13, 7
	s_add_u32 s6, s45, 0x9800000
	s_mov_b64 s[8:9], 0x80
	s_addc_u32 s7, s46, 0
	s_add_i32 m0, s19, 0x18000
	v_lshl_add_u64 v[6:7], v[6:7], 0, s[8:9]
	s_waitcnt vmcnt(4)
	s_mov_b32 s94, 0
	s_barrier
	global_load_lds_dwordx4 v[6:7], off
	v_lshl_add_u64 v[4:5], v[4:5], 0, s[8:9]
	s_add_i32 m0, s19, 0x1a000
	s_add_i32 s45, s19, 0x8000
	s_add_i32 s46, s19, 0xa000
	global_load_lds_dwordx4 v[4:5], off
	v_lshl_add_u64 v[2:3], v[2:3], 0, s[8:9]
	s_mov_b32 m0, s45
	s_add_u32 s10, s26, 0x40080
	global_load_lds_dwordx4 v[2:3], off
	v_lshl_add_u64 v[0:1], v[0:1], 0, s[8:9]
	s_mov_b32 m0, s46
	s_addc_u32 s11, s27, 0
	global_load_lds_dwordx4 v[0:1], off
	s_add_i32 m0, s19, 0x1c000
	v_lshl_add_u64 v[0:1], s[10:11], 0, v[132:133]
	global_load_lds_dwordx4 v[0:1], off
	v_lshl_add_u64 v[0:1], s[10:11], 0, v[128:129]
	s_add_i32 m0, s19, 0x1e000
	s_sext_i32_i16 s52, s4
	global_load_lds_dwordx4 v[0:1], off
	v_lshrrev_b32_e32 v1, 1, v145
	v_and_b32_e32 v1, 24, v1
	s_lshl_b32 s4, s5, 8
	v_and_b32_e32 v0, 15, v145
	v_lshlrev_b32_e32 v2, 1, v1
	s_add_i32 s4, s4, 0
	v_lshl_or_b32 v144, s5, 6, v0
	v_lshl_or_b32 v2, v0, 6, v2
	v_lshlrev_b32_e32 v0, 2, v0
	s_add_i32 s4, s4, 0x20000
	v_and_b32_e32 v3, 32, v0
	v_add_u32_e32 v146, s4, v0
	v_lshlrev_b32_e32 v0, 14, v12
	v_and_b32_e32 v0, 0xffff8000, v0
	v_or_b32_e32 v147, s13, v1
	v_lshl_add_u32 v0, v11, 11, v0
	v_and_b32_e32 v1, 1, v12
	v_lshl_or_b32 v0, v1, 6, v0
	v_lshl_add_u32 v136, v13, 1, v0
	v_lshlrev_b32_e32 v0, 14, v8
	v_and_b32_e32 v0, 0xffff8000, v0
	s_waitcnt vmcnt(6)
	v_lshl_add_u32 v0, v9, 11, v0
	v_and_b32_e32 v1, 1, v8
	v_bitop3_b32 v4, v2, s12, v3 bitop3:0xde
	v_bitop3_b32 v145, s14, v2, v3 bitop3:0xf6
	v_lshl_or_b32 v0, v1, 6, v0
	s_add_i32 s47, 0, 0x10000
	s_add_i32 s48, 0, 0x14000
	v_mov_b32_e32 v137, v133
	v_lshl_add_u32 v138, v10, 1, v0
	v_mov_b32_e32 v139, v133
	v_mov_b64_e32 v[140:141], 0x1080
	v_mov_b64_e32 v[142:143], 0x107f
	v_add_u32_e32 v148, s47, v145
	v_add_u32_e32 v149, 0, v4
	v_add_u32_e32 v150, s48, v145
	s_movk_i32 s49, 0x1600
	s_barrier

.Lg893_noy:
	ds_read_b128 v[152:155], v148
	ds_read_b128 v[156:159], v148 offset:1024
	ds_read_b128 v[160:163], v148 offset:2048
	ds_read_b128 v[164:167], v148 offset:3072
	s_add_u32 s26, s20, 0xfffc0080
	s_addc_u32 s27, s21, -1
	s_cmp_eq_u32 s57, 12
	s_cselect_b32 s29, s13, s27
	s_cselect_b32 s28, s53, s26
	s_cselect_b32 s27, s11, s56
	s_cselect_b32 s26, s54, s55
	s_add_i32 m0, s19, 0xc000
	ds_read_b128 v[168:171], v149
	ds_read_b128 v[172:175], v149 offset:1024
	ds_read_b128 v[176:179], v149 offset:2048
	ds_read_b128 v[180:183], v149 offset:3072
	ds_read_b128 v[184:187], v149 offset:4096
	ds_read_b128 v[188:191], v149 offset:5120
	ds_read_b128 v[192:195], v149 offset:6144
	ds_read_b128 v[196:199], v149 offset:7168
	global_load_lds_dwordx4 v136, s[20:21]
	s_add_i32 m0, s19, 0xe000
	s_nop 0
	global_load_lds_dwordx4 v138, s[20:21]
	s_waitcnt lgkmcnt(8)
	s_barrier
	s_waitcnt lgkmcnt(0)
	s_waitcnt lgkmcnt(0)
	v_mfma_f32_16x16x32_bf16 v[124:127], v[152:155], v[168:171], 0
	v_mfma_f32_16x16x32_bf16 v[120:123], v[160:163], v[168:171], 0
	v_mfma_f32_16x16x32_bf16 v[108:111], v[152:155], v[176:179], 0
	v_mfma_f32_16x16x32_bf16 v[104:107], v[160:163], v[176:179], 0
	v_mfma_f32_16x16x32_bf16 v[92:95], v[152:155], v[184:187], 0
	v_mfma_f32_16x16x32_bf16 v[88:91], v[160:163], v[184:187], 0
	v_mfma_f32_16x16x32_bf16 v[76:79], v[152:155], v[192:195], 0
	v_mfma_f32_16x16x32_bf16 v[72:75], v[160:163], v[192:195], 0
	v_mfma_f32_16x16x32_bf16 v[124:127], v[156:159], v[172:175], v[124:127]
	v_mfma_f32_16x16x32_bf16 v[120:123], v[164:167], v[172:175], v[120:123]
	v_mfma_f32_16x16x32_bf16 v[108:111], v[156:159], v[180:183], v[108:111]
	v_mfma_f32_16x16x32_bf16 v[104:107], v[164:167], v[180:183], v[104:107]
	v_mfma_f32_16x16x32_bf16 v[92:95], v[156:159], v[188:191], v[92:95]
	v_mfma_f32_16x16x32_bf16 v[88:91], v[164:167], v[188:191], v[88:91]
	v_mfma_f32_16x16x32_bf16 v[76:79], v[156:159], v[196:199], v[76:79]
	v_mfma_f32_16x16x32_bf16 v[72:75], v[164:167], v[196:199], v[72:75]
	s_barrier
	s_add_i32 s58, s47, s31
	s_add_u32 s80, s26, 0x80
	s_addc_u32 s81, s27, 0
	s_mov_b32 m0, s58
	ds_read_b128 v[200:203], v150
	ds_read_b128 v[204:207], v150 offset:1024
	ds_read_b128 v[208:211], v150 offset:2048
	ds_read_b128 v[212:215], v150 offset:3072
	global_load_lds_dwordx4 v132, s[26:27]
	s_add_i32 m0, s58, 0x2000
	s_nop 0
	global_load_lds_dwordx4 v128, s[26:27]
	s_cmp_lg_u32 s94, 0
	s_cbranch_scc1 .Lpw893_0a
	s_waitcnt vmcnt(10)
	s_branch .Lpw893_0b

.Lpw893_0b:
	s_barrier
	s_waitcnt lgkmcnt(0)
	s_waitcnt lgkmcnt(0)
	v_mfma_f32_16x16x32_bf16 v[116:119], v[200:203], v[168:171], 0
	v_mfma_f32_16x16x32_bf16 v[112:115], v[208:211], v[168:171], 0
	v_mfma_f32_16x16x32_bf16 v[100:103], v[200:203], v[176:179], 0
	v_mfma_f32_16x16x32_bf16 v[96:99], v[208:211], v[176:179], 0
	v_mfma_f32_16x16x32_bf16 v[84:87], v[200:203], v[184:187], 0
	v_mfma_f32_16x16x32_bf16 v[80:83], v[208:211], v[184:187], 0
	v_mfma_f32_16x16x32_bf16 v[68:71], v[200:203], v[192:195], 0
	v_mfma_f32_16x16x32_bf16 v[64:67], v[208:211], v[192:195], 0
	v_mfma_f32_16x16x32_bf16 v[116:119], v[204:207], v[172:175], v[116:119]
	v_mfma_f32_16x16x32_bf16 v[112:115], v[212:215], v[172:175], v[112:115]
	v_mfma_f32_16x16x32_bf16 v[100:103], v[204:207], v[180:183], v[100:103]
	v_mfma_f32_16x16x32_bf16 v[96:99], v[212:215], v[180:183], v[96:99]
	v_mfma_f32_16x16x32_bf16 v[84:87], v[204:207], v[188:191], v[84:87]
	v_mfma_f32_16x16x32_bf16 v[80:83], v[212:215], v[188:191], v[80:83]
	v_mfma_f32_16x16x32_bf16 v[68:71], v[204:207], v[196:199], v[68:71]
	v_mfma_f32_16x16x32_bf16 v[64:67], v[212:215], v[196:199], v[64:67]
	s_mov_b32 m0, s19
	s_add_u32 s82, s28, 0x80
	s_addc_u32 s83, s29, 0
	s_barrier
	ds_read_b128 v[168:171], v149 offset:16384
	ds_read_b128 v[172:175], v149 offset:17408
	ds_read_b128 v[176:179], v149 offset:18432
	ds_read_b128 v[180:183], v149 offset:19456
	ds_read_b128 v[184:187], v149 offset:20480
	ds_read_b128 v[188:191], v149 offset:21504
	ds_read_b128 v[192:195], v149 offset:22528
	ds_read_b128 v[196:199], v149 offset:23552
	global_load_lds_dwordx4 v134, s[28:29]
	s_mov_b32 m0, s42
	s_nop 0
	global_load_lds_dwordx4 v130, s[28:29]
	s_barrier
	s_waitcnt lgkmcnt(0)
	s_waitcnt lgkmcnt(0)
	v_mfma_f32_16x16x32_bf16 v[60:63], v[152:155], v[168:171], 0
	v_mfma_f32_16x16x32_bf16 v[56:59], v[160:163], v[168:171], 0
	v_mfma_f32_16x16x32_bf16 v[44:47], v[152:155], v[176:179], 0
	v_mfma_f32_16x16x32_bf16 v[40:43], v[160:163], v[176:179], 0
	v_mfma_f32_16x16x32_bf16 v[28:31], v[152:155], v[184:187], 0
	v_mfma_f32_16x16x32_bf16 v[24:27], v[160:163], v[184:187], 0
	v_mfma_f32_16x16x32_bf16 v[12:15], v[152:155], v[192:195], 0
	v_mfma_f32_16x16x32_bf16 v[8:11], v[160:163], v[192:195], 0
	v_mfma_f32_16x16x32_bf16 v[60:63], v[156:159], v[172:175], v[60:63]
	v_mfma_f32_16x16x32_bf16 v[56:59], v[164:167], v[172:175], v[56:59]
	v_mfma_f32_16x16x32_bf16 v[44:47], v[156:159], v[180:183], v[44:47]
	v_mfma_f32_16x16x32_bf16 v[40:43], v[164:167], v[180:183], v[40:43]
	v_mfma_f32_16x16x32_bf16 v[28:31], v[156:159], v[188:191], v[28:31]
	v_mfma_f32_16x16x32_bf16 v[24:27], v[164:167], v[188:191], v[24:27]
	v_mfma_f32_16x16x32_bf16 v[12:15], v[156:159], v[196:199], v[12:15]
	v_mfma_f32_16x16x32_bf16 v[8:11], v[164:167], v[196:199], v[8:11]
	s_barrier
	s_add_u32 s58, s26, 0x40000
	s_addc_u32 s59, s27, 0
	s_add_i32 s60, s48, s31
	s_mov_b32 m0, s60
	s_nop 0
	global_load_lds_dwordx4 v132, s[58:59]
	s_add_i32 m0, s60, 0x2000
	s_nop 0
	global_load_lds_dwordx4 v128, s[58:59]
	s_cmp_lg_u32 s94, 0
	s_cbranch_scc1 .Lpw893_1a
	s_waitcnt vmcnt(8)
	s_branch .Lpw893_1b

.Lpw893_1b:
	s_barrier
	v_mfma_f32_16x16x32_bf16 v[52:55], v[200:203], v[168:171], 0
	v_mfma_f32_16x16x32_bf16 v[48:51], v[208:211], v[168:171], 0
	v_mfma_f32_16x16x32_bf16 v[36:39], v[200:203], v[176:179], 0
	v_mfma_f32_16x16x32_bf16 v[32:35], v[208:211], v[176:179], 0
	v_mfma_f32_16x16x32_bf16 v[20:23], v[200:203], v[184:187], 0
	v_mfma_f32_16x16x32_bf16 v[16:19], v[208:211], v[184:187], 0
	v_mfma_f32_16x16x32_bf16 v[4:7], v[200:203], v[192:195], 0
	v_mfma_f32_16x16x32_bf16 v[0:3], v[208:211], v[192:195], 0
	v_mfma_f32_16x16x32_bf16 v[52:55], v[204:207], v[172:175], v[52:55]
	v_mfma_f32_16x16x32_bf16 v[48:51], v[212:215], v[172:175], v[48:51]
	v_mfma_f32_16x16x32_bf16 v[36:39], v[204:207], v[180:183], v[36:39]
	v_mfma_f32_16x16x32_bf16 v[32:35], v[212:215], v[180:183], v[32:35]
	v_mfma_f32_16x16x32_bf16 v[20:23], v[204:207], v[188:191], v[20:23]
	v_mfma_f32_16x16x32_bf16 v[16:19], v[212:215], v[188:191], v[16:19]
	v_mfma_f32_16x16x32_bf16 v[4:7], v[204:207], v[196:199], v[4:7]
	v_mfma_f32_16x16x32_bf16 v[0:3], v[212:215], v[196:199], v[0:3]
	s_add_i32 s58, 0, 0x18000
	v_add_u32_e32 v151, s58, v145
	s_barrier
	s_branch .Lg893_mid

.Lg893_nox:
	s_mov_b32 s94, 1
	v_lshl_add_u32 v180, s51, 10, v146
	ds_read2_b32 v[152:153], v180 offset1:16
	ds_read2_b32 v[154:155], v180 offset0:32 offset1:48
	ds_read2_b32 v[156:157], v180 offset0:128 offset1:144
	ds_read2_b32 v[158:159], v180 offset0:160 offset1:176
	v_lshl_or_b32 v181, s52, 7, v147
	v_lshl_add_u32 v182, s18, 8, v144
	s_and_b64 vcc, exec, s[4:5]
	s_mov_b32 s52, s10
	s_mov_b32 s18, s12
	s_mov_b64 s[26:27], s[16:17]
	s_mov_b32 s51, s50
	s_mov_b64 s[20:21], s[14:15]
	v_mul_u32_u24_e32 v183, s49, v182
	v_lshl_add_u32 v183, v181, 1, v183
	s_waitcnt lgkmcnt(0)
	v_mul_f32_e32 v176, 0xbfb8aa3b, v152
	v_mul_f32_e32 v177, v152, v152
	v_rcp_f32_e32 v178, v177
	v_pk_mul_f32 v[160:161], v[124:125], v[176:177] op_sel_hi:[1,0]
	v_pk_mul_f32 v[162:163], v[126:127], v[176:177] op_sel_hi:[1,0]
	v_pk_mul_f32 v[164:165], v[120:121], v[176:177] op_sel_hi:[1,0]
	v_pk_mul_f32 v[166:167], v[122:123], v[176:177] op_sel_hi:[1,0]
	v_exp_f32_e32 v160, v160
	v_exp_f32_e32 v161, v161
	v_exp_f32_e32 v162, v162
	v_exp_f32_e32 v163, v163
	v_exp_f32_e32 v164, v164
	v_exp_f32_e32 v165, v165
	v_exp_f32_e32 v166, v166
	v_exp_f32_e32 v167, v167
	v_pk_fma_f32 v[160:161], v[160:161], v[178:179], v[178:179] op_sel_hi:[1,0,0]
	v_pk_fma_f32 v[162:163], v[162:163], v[178:179], v[178:179] op_sel_hi:[1,0,0]
	v_pk_fma_f32 v[164:165], v[164:165], v[178:179], v[178:179] op_sel_hi:[1,0,0]
	v_pk_fma_f32 v[166:167], v[166:167], v[178:179], v[178:179] op_sel_hi:[1,0,0]
	v_rcp_f32_e32 v160, v160
	v_rcp_f32_e32 v161, v161
	v_rcp_f32_e32 v162, v162
	v_rcp_f32_e32 v163, v163
	v_rcp_f32_e32 v164, v164
	v_rcp_f32_e32 v165, v165
	v_rcp_f32_e32 v166, v166
	v_rcp_f32_e32 v167, v167
	v_pk_mul_f32 v[124:125], v[124:125], v[116:117]
	v_pk_mul_f32 v[126:127], v[126:127], v[118:119]
	v_pk_mul_f32 v[120:121], v[120:121], v[112:113]
	v_pk_mul_f32 v[122:123], v[122:123], v[114:115]
	v_pk_mul_f32 v[124:125], v[124:125], v[160:161]
	v_pk_mul_f32 v[126:127], v[126:127], v[162:163]
	v_pk_mul_f32 v[120:121], v[120:121], v[164:165]
	v_pk_mul_f32 v[122:123], v[122:123], v[166:167]
	v_cvt_pk_bf16_f32 v168, v124, v125
	v_cvt_pk_bf16_f32 v169, v126, v127
	v_cvt_pk_bf16_f32 v170, v120, v121
	v_cvt_pk_bf16_f32 v171, v122, v123
	global_store_dwordx4 v183, v[168:171], s[6:7]
	v_mul_f32_e32 v176, 0xbfb8aa3b, v153
	v_mul_f32_e32 v177, v153, v153
	v_rcp_f32_e32 v178, v177
	v_pk_mul_f32 v[160:161], v[108:109], v[176:177] op_sel_hi:[1,0]
	v_pk_mul_f32 v[162:163], v[110:111], v[176:177] op_sel_hi:[1,0]
	v_pk_mul_f32 v[164:165], v[104:105], v[176:177] op_sel_hi:[1,0]
	v_pk_mul_f32 v[166:167], v[106:107], v[176:177] op_sel_hi:[1,0]
	v_exp_f32_e32 v160, v160
	v_exp_f32_e32 v161, v161
	v_exp_f32_e32 v162, v162
	v_exp_f32_e32 v163, v163
	v_exp_f32_e32 v164, v164
	v_exp_f32_e32 v165, v165
	v_exp_f32_e32 v166, v166
	v_exp_f32_e32 v167, v167
	v_pk_fma_f32 v[160:161], v[160:161], v[178:179], v[178:179] op_sel_hi:[1,0,0]
	v_pk_fma_f32 v[162:163], v[162:163], v[178:179], v[178:179] op_sel_hi:[1,0,0]
	v_pk_fma_f32 v[164:165], v[164:165], v[178:179], v[178:179] op_sel_hi:[1,0,0]
	v_pk_fma_f32 v[166:167], v[166:167], v[178:179], v[178:179] op_sel_hi:[1,0,0]
	v_rcp_f32_e32 v160, v160
	v_rcp_f32_e32 v161, v161
	v_rcp_f32_e32 v162, v162
	v_rcp_f32_e32 v163, v163
	v_rcp_f32_e32 v164, v164
	v_rcp_f32_e32 v165, v165
	v_rcp_f32_e32 v166, v166
	v_rcp_f32_e32 v167, v167
	v_pk_mul_f32 v[108:109], v[108:109], v[100:101]
	v_pk_mul_f32 v[110:111], v[110:111], v[102:103]
	v_pk_mul_f32 v[104:105], v[104:105], v[96:97]
	v_pk_mul_f32 v[106:107], v[106:107], v[98:99]
	v_pk_mul_f32 v[108:109], v[108:109], v[160:161]
	v_pk_mul_f32 v[110:111], v[110:111], v[162:163]
	v_pk_mul_f32 v[104:105], v[104:105], v[164:165]
	v_pk_mul_f32 v[106:107], v[106:107], v[166:167]
	v_cvt_pk_bf16_f32 v172, v108, v109
	v_cvt_pk_bf16_f32 v173, v110, v111
	v_cvt_pk_bf16_f32 v174, v104, v105
	v_cvt_pk_bf16_f32 v175, v106, v107
	v_add_u32_e32 v185, 0x16000, v183
	global_store_dwordx4 v185, v[172:175], s[6:7]
	v_mul_f32_e32 v176, 0xbfb8aa3b, v154
	v_mul_f32_e32 v177, v154, v154
	v_rcp_f32_e32 v178, v177
	v_pk_mul_f32 v[160:161], v[92:93], v[176:177] op_sel_hi:[1,0]
	v_pk_mul_f32 v[162:163], v[94:95], v[176:177] op_sel_hi:[1,0]
	v_pk_mul_f32 v[164:165], v[88:89], v[176:177] op_sel_hi:[1,0]
	v_pk_mul_f32 v[166:167], v[90:91], v[176:177] op_sel_hi:[1,0]
	v_exp_f32_e32 v160, v160
	v_exp_f32_e32 v161, v161
	v_exp_f32_e32 v162, v162
	v_exp_f32_e32 v163, v163
	v_exp_f32_e32 v164, v164
	v_exp_f32_e32 v165, v165
	v_exp_f32_e32 v166, v166
	v_exp_f32_e32 v167, v167
	v_pk_fma_f32 v[160:161], v[160:161], v[178:179], v[178:179] op_sel_hi:[1,0,0]
	v_pk_fma_f32 v[162:163], v[162:163], v[178:179], v[178:179] op_sel_hi:[1,0,0]
	v_pk_fma_f32 v[164:165], v[164:165], v[178:179], v[178:179] op_sel_hi:[1,0,0]
	v_pk_fma_f32 v[166:167], v[166:167], v[178:179], v[178:179] op_sel_hi:[1,0,0]
	v_rcp_f32_e32 v160, v160
	v_rcp_f32_e32 v161, v161
	v_rcp_f32_e32 v162, v162
	v_rcp_f32_e32 v163, v163
	v_rcp_f32_e32 v164, v164
	v_rcp_f32_e32 v165, v165
	v_rcp_f32_e32 v166, v166
	v_rcp_f32_e32 v167, v167
	v_pk_mul_f32 v[92:93], v[92:93], v[84:85]
	v_pk_mul_f32 v[94:95], v[94:95], v[86:87]
	v_pk_mul_f32 v[88:89], v[88:89], v[80:81]
	v_pk_mul_f32 v[90:91], v[90:91], v[82:83]
	v_pk_mul_f32 v[92:93], v[92:93], v[160:161]
	v_pk_mul_f32 v[94:95], v[94:95], v[162:163]
	v_pk_mul_f32 v[88:89], v[88:89], v[164:165]
	v_pk_mul_f32 v[90:91], v[90:91], v[166:167]
	v_cvt_pk_bf16_f32 v168, v92, v93
	v_cvt_pk_bf16_f32 v169, v94, v95
	v_cvt_pk_bf16_f32 v170, v88, v89
	v_cvt_pk_bf16_f32 v171, v90, v91
	v_add_u32_e32 v184, 0x2c000, v183
	global_store_dwordx4 v184, v[168:171], s[6:7]
	v_mul_f32_e32 v176, 0xbfb8aa3b, v155
	v_mul_f32_e32 v177, v155, v155
	v_rcp_f32_e32 v178, v177
	v_pk_mul_f32 v[160:161], v[76:77], v[176:177] op_sel_hi:[1,0]
	v_pk_mul_f32 v[162:163], v[78:79], v[176:177] op_sel_hi:[1,0]
	v_pk_mul_f32 v[164:165], v[72:73], v[176:177] op_sel_hi:[1,0]
	v_pk_mul_f32 v[166:167], v[74:75], v[176:177] op_sel_hi:[1,0]
	v_exp_f32_e32 v160, v160
	v_exp_f32_e32 v161, v161
	v_exp_f32_e32 v162, v162
	v_exp_f32_e32 v163, v163
	v_exp_f32_e32 v164, v164
	v_exp_f32_e32 v165, v165
	v_exp_f32_e32 v166, v166
	v_exp_f32_e32 v167, v167
	v_pk_fma_f32 v[160:161], v[160:161], v[178:179], v[178:179] op_sel_hi:[1,0,0]
	v_pk_fma_f32 v[162:163], v[162:163], v[178:179], v[178:179] op_sel_hi:[1,0,0]
	v_pk_fma_f32 v[164:165], v[164:165], v[178:179], v[178:179] op_sel_hi:[1,0,0]
	v_pk_fma_f32 v[166:167], v[166:167], v[178:179], v[178:179] op_sel_hi:[1,0,0]
	v_rcp_f32_e32 v160, v160
	v_rcp_f32_e32 v161, v161
	v_rcp_f32_e32 v162, v162
	v_rcp_f32_e32 v163, v163
	v_rcp_f32_e32 v164, v164
	v_rcp_f32_e32 v165, v165
	v_rcp_f32_e32 v166, v166
	v_rcp_f32_e32 v167, v167
	v_pk_mul_f32 v[76:77], v[76:77], v[68:69]
	v_pk_mul_f32 v[78:79], v[78:79], v[70:71]
	v_pk_mul_f32 v[72:73], v[72:73], v[64:65]
	v_pk_mul_f32 v[74:75], v[74:75], v[66:67]
	v_pk_mul_f32 v[76:77], v[76:77], v[160:161]
	v_pk_mul_f32 v[78:79], v[78:79], v[162:163]
	v_pk_mul_f32 v[72:73], v[72:73], v[164:165]
	v_pk_mul_f32 v[74:75], v[74:75], v[166:167]
	v_cvt_pk_bf16_f32 v172, v76, v77
	v_cvt_pk_bf16_f32 v173, v78, v79
	v_cvt_pk_bf16_f32 v174, v72, v73
	v_cvt_pk_bf16_f32 v175, v74, v75
	v_add_u32_e32 v185, 0x42000, v183
	global_store_dwordx4 v185, v[172:175], s[6:7]
	v_mul_f32_e32 v176, 0xbfb8aa3b, v156
	v_mul_f32_e32 v177, v156, v156
	v_rcp_f32_e32 v178, v177
	v_pk_mul_f32 v[160:161], v[60:61], v[176:177] op_sel_hi:[1,0]
	v_pk_mul_f32 v[162:163], v[62:63], v[176:177] op_sel_hi:[1,0]
	v_pk_mul_f32 v[164:165], v[56:57], v[176:177] op_sel_hi:[1,0]
	v_pk_mul_f32 v[166:167], v[58:59], v[176:177] op_sel_hi:[1,0]
	v_exp_f32_e32 v160, v160
	v_exp_f32_e32 v161, v161
	v_exp_f32_e32 v162, v162
	v_exp_f32_e32 v163, v163
	v_exp_f32_e32 v164, v164
	v_exp_f32_e32 v165, v165
	v_exp_f32_e32 v166, v166
	v_exp_f32_e32 v167, v167
	v_pk_fma_f32 v[160:161], v[160:161], v[178:179], v[178:179] op_sel_hi:[1,0,0]
	v_pk_fma_f32 v[162:163], v[162:163], v[178:179], v[178:179] op_sel_hi:[1,0,0]
	v_pk_fma_f32 v[164:165], v[164:165], v[178:179], v[178:179] op_sel_hi:[1,0,0]
	v_pk_fma_f32 v[166:167], v[166:167], v[178:179], v[178:179] op_sel_hi:[1,0,0]
	v_rcp_f32_e32 v160, v160
	v_rcp_f32_e32 v161, v161
	v_rcp_f32_e32 v162, v162
	v_rcp_f32_e32 v163, v163
	v_rcp_f32_e32 v164, v164
	v_rcp_f32_e32 v165, v165
	v_rcp_f32_e32 v166, v166
	v_rcp_f32_e32 v167, v167
	v_pk_mul_f32 v[60:61], v[60:61], v[52:53]
	v_pk_mul_f32 v[62:63], v[62:63], v[54:55]
	v_pk_mul_f32 v[56:57], v[56:57], v[48:49]
	v_pk_mul_f32 v[58:59], v[58:59], v[50:51]
	v_pk_mul_f32 v[60:61], v[60:61], v[160:161]
	v_pk_mul_f32 v[62:63], v[62:63], v[162:163]
	v_pk_mul_f32 v[56:57], v[56:57], v[164:165]
	v_pk_mul_f32 v[58:59], v[58:59], v[166:167]
	v_cvt_pk_bf16_f32 v168, v60, v61
	v_cvt_pk_bf16_f32 v169, v62, v63
	v_cvt_pk_bf16_f32 v170, v56, v57
	v_cvt_pk_bf16_f32 v171, v58, v59
	v_add_u32_e32 v184, 0xb0000, v183
	global_store_dwordx4 v184, v[168:171], s[6:7]
	v_mul_f32_e32 v176, 0xbfb8aa3b, v157
	v_mul_f32_e32 v177, v157, v157
	v_rcp_f32_e32 v178, v177
	v_pk_mul_f32 v[160:161], v[44:45], v[176:177] op_sel_hi:[1,0]
	v_pk_mul_f32 v[162:163], v[46:47], v[176:177] op_sel_hi:[1,0]
	v_pk_mul_f32 v[164:165], v[40:41], v[176:177] op_sel_hi:[1,0]
	v_pk_mul_f32 v[166:167], v[42:43], v[176:177] op_sel_hi:[1,0]
	v_exp_f32_e32 v160, v160
	v_exp_f32_e32 v161, v161
	v_exp_f32_e32 v162, v162
	v_exp_f32_e32 v163, v163
	v_exp_f32_e32 v164, v164
	v_exp_f32_e32 v165, v165
	v_exp_f32_e32 v166, v166
	v_exp_f32_e32 v167, v167
	v_pk_fma_f32 v[160:161], v[160:161], v[178:179], v[178:179] op_sel_hi:[1,0,0]
	v_pk_fma_f32 v[162:163], v[162:163], v[178:179], v[178:179] op_sel_hi:[1,0,0]
	v_pk_fma_f32 v[164:165], v[164:165], v[178:179], v[178:179] op_sel_hi:[1,0,0]
	v_pk_fma_f32 v[166:167], v[166:167], v[178:179], v[178:179] op_sel_hi:[1,0,0]
	v_rcp_f32_e32 v160, v160
	v_rcp_f32_e32 v161, v161
	v_rcp_f32_e32 v162, v162
	v_rcp_f32_e32 v163, v163
	v_rcp_f32_e32 v164, v164
	v_rcp_f32_e32 v165, v165
	v_rcp_f32_e32 v166, v166
	v_rcp_f32_e32 v167, v167
	v_pk_mul_f32 v[44:45], v[44:45], v[36:37]
	v_pk_mul_f32 v[46:47], v[46:47], v[38:39]
	v_pk_mul_f32 v[40:41], v[40:41], v[32:33]
	v_pk_mul_f32 v[42:43], v[42:43], v[34:35]
	v_pk_mul_f32 v[44:45], v[44:45], v[160:161]
	v_pk_mul_f32 v[46:47], v[46:47], v[162:163]
	v_pk_mul_f32 v[40:41], v[40:41], v[164:165]
	v_pk_mul_f32 v[42:43], v[42:43], v[166:167]
	v_cvt_pk_bf16_f32 v172, v44, v45
	v_cvt_pk_bf16_f32 v173, v46, v47
	v_cvt_pk_bf16_f32 v174, v40, v41
	v_cvt_pk_bf16_f32 v175, v42, v43
	v_add_u32_e32 v185, 0xc6000, v183
	global_store_dwordx4 v185, v[172:175], s[6:7]
	v_mul_f32_e32 v176, 0xbfb8aa3b, v158
	v_mul_f32_e32 v177, v158, v158
	v_rcp_f32_e32 v178, v177
	v_pk_mul_f32 v[160:161], v[28:29], v[176:177] op_sel_hi:[1,0]
	v_pk_mul_f32 v[162:163], v[30:31], v[176:177] op_sel_hi:[1,0]
	v_pk_mul_f32 v[164:165], v[24:25], v[176:177] op_sel_hi:[1,0]
	v_pk_mul_f32 v[166:167], v[26:27], v[176:177] op_sel_hi:[1,0]
	v_exp_f32_e32 v160, v160
	v_exp_f32_e32 v161, v161
	v_exp_f32_e32 v162, v162
	v_exp_f32_e32 v163, v163
	v_exp_f32_e32 v164, v164
	v_exp_f32_e32 v165, v165
	v_exp_f32_e32 v166, v166
	v_exp_f32_e32 v167, v167
	v_pk_fma_f32 v[160:161], v[160:161], v[178:179], v[178:179] op_sel_hi:[1,0,0]
	v_pk_fma_f32 v[162:163], v[162:163], v[178:179], v[178:179] op_sel_hi:[1,0,0]
	v_pk_fma_f32 v[164:165], v[164:165], v[178:179], v[178:179] op_sel_hi:[1,0,0]
	v_pk_fma_f32 v[166:167], v[166:167], v[178:179], v[178:179] op_sel_hi:[1,0,0]
	v_rcp_f32_e32 v160, v160
	v_rcp_f32_e32 v161, v161
	v_rcp_f32_e32 v162, v162
	v_rcp_f32_e32 v163, v163
	v_rcp_f32_e32 v164, v164
	v_rcp_f32_e32 v165, v165
	v_rcp_f32_e32 v166, v166
	v_rcp_f32_e32 v167, v167
	v_pk_mul_f32 v[28:29], v[28:29], v[20:21]
	v_pk_mul_f32 v[30:31], v[30:31], v[22:23]
	v_pk_mul_f32 v[24:25], v[24:25], v[16:17]
	v_pk_mul_f32 v[26:27], v[26:27], v[18:19]
	v_pk_mul_f32 v[28:29], v[28:29], v[160:161]
	v_pk_mul_f32 v[30:31], v[30:31], v[162:163]
	v_pk_mul_f32 v[24:25], v[24:25], v[164:165]
	v_pk_mul_f32 v[26:27], v[26:27], v[166:167]
	v_cvt_pk_bf16_f32 v168, v28, v29
	v_cvt_pk_bf16_f32 v169, v30, v31
	v_cvt_pk_bf16_f32 v170, v24, v25
	v_cvt_pk_bf16_f32 v171, v26, v27
	v_add_u32_e32 v184, 0xdc000, v183
	global_store_dwordx4 v184, v[168:171], s[6:7]
	v_mul_f32_e32 v176, 0xbfb8aa3b, v159
	v_mul_f32_e32 v177, v159, v159
	v_rcp_f32_e32 v178, v177
	v_pk_mul_f32 v[160:161], v[12:13], v[176:177] op_sel_hi:[1,0]
	v_pk_mul_f32 v[162:163], v[14:15], v[176:177] op_sel_hi:[1,0]
	v_pk_mul_f32 v[164:165], v[8:9], v[176:177] op_sel_hi:[1,0]
	v_pk_mul_f32 v[166:167], v[10:11], v[176:177] op_sel_hi:[1,0]
	v_exp_f32_e32 v160, v160
	v_exp_f32_e32 v161, v161
	v_exp_f32_e32 v162, v162
	v_exp_f32_e32 v163, v163
	v_exp_f32_e32 v164, v164
	v_exp_f32_e32 v165, v165
	v_exp_f32_e32 v166, v166
	v_exp_f32_e32 v167, v167
	v_pk_fma_f32 v[160:161], v[160:161], v[178:179], v[178:179] op_sel_hi:[1,0,0]
	v_pk_fma_f32 v[162:163], v[162:163], v[178:179], v[178:179] op_sel_hi:[1,0,0]
	v_pk_fma_f32 v[164:165], v[164:165], v[178:179], v[178:179] op_sel_hi:[1,0,0]
	v_pk_fma_f32 v[166:167], v[166:167], v[178:179], v[178:179] op_sel_hi:[1,0,0]
	v_rcp_f32_e32 v160, v160
	v_rcp_f32_e32 v161, v161
	v_rcp_f32_e32 v162, v162
	v_rcp_f32_e32 v163, v163
	v_rcp_f32_e32 v164, v164
	v_rcp_f32_e32 v165, v165
	v_rcp_f32_e32 v166, v166
	v_rcp_f32_e32 v167, v167
	v_pk_mul_f32 v[12:13], v[12:13], v[4:5]
	v_pk_mul_f32 v[14:15], v[14:15], v[6:7]
	v_pk_mul_f32 v[8:9], v[8:9], v[0:1]
	v_pk_mul_f32 v[10:11], v[10:11], v[2:3]
	v_pk_mul_f32 v[12:13], v[12:13], v[160:161]
	v_pk_mul_f32 v[14:15], v[14:15], v[162:163]
	v_pk_mul_f32 v[8:9], v[8:9], v[164:165]
	v_pk_mul_f32 v[10:11], v[10:11], v[166:167]
	v_cvt_pk_bf16_f32 v172, v12, v13
	v_cvt_pk_bf16_f32 v173, v14, v15
	v_cvt_pk_bf16_f32 v174, v8, v9
	v_cvt_pk_bf16_f32 v175, v10, v11
	v_add_u32_e32 v185, 0xf2000, v183
	global_store_dwordx4 v185, v[172:175], s[6:7]
	s_cbranch_vccz .LBB0_890
	s_waitcnt vmcnt(0)
	s_cmpk_gt_u32 s30, 0xff
	s_cbranch_scc1 .LBB0_897

.LBB0_964:
	s_add_u32 s12, s4, 0x3800000
	s_addc_u32 s13, s5, 0
	s_add_u32 s14, s4, 0x3300000
	s_addc_u32 s15, s5, 0
	s_add_u32 s16, s4, 0x3798b00
	s_mov_b64 s[18:19], 0x80
	s_addc_u32 s17, s5, 0
	s_and_b32 s41, s3, 3
	s_add_i32 m0, s37, 0x18000
	v_lshl_add_u64 v[6:7], v[6:7], 0, s[18:19]
	s_lshl_b32 s3, s6, 13
	s_lshl_b32 s4, s41, 12
	s_waitcnt vmcnt(4)
	s_mov_b32 s94, 0
	s_barrier
	global_load_lds_dwordx4 v[6:7], off
	v_lshl_add_u64 v[4:5], v[4:5], 0, s[18:19]
	s_add_i32 m0, s37, 0x1a000
	s_add_i32 s42, s37, 0x8000
	s_add_i32 s43, s37, 0xa000
	global_load_lds_dwordx4 v[4:5], off
	v_lshl_add_u64 v[2:3], v[2:3], 0, s[18:19]
	s_mov_b32 m0, s42
	s_add_u32 s0, s22, 0xb0080
	global_load_lds_dwordx4 v[2:3], off
	v_lshl_add_u64 v[0:1], v[0:1], 0, s[18:19]
	s_mov_b32 m0, s43
	s_addc_u32 s1, s23, 0
	global_load_lds_dwordx4 v[0:1], off
	s_add_i32 m0, s37, 0x1c000
	v_lshl_add_u64 v[0:1], s[0:1], 0, v[130:131]
	global_load_lds_dwordx4 v[0:1], off
	v_lshl_add_u64 v[0:1], s[0:1], 0, v[134:135]
	s_add_i32 m0, s37, 0x1e000
	v_bfe_u32 v2, v240, 4, 2
	global_load_lds_dwordx4 v[0:1], off
	v_and_b32_e32 v1, 15, v240
	v_lshlrev_b32_e32 v0, 4, v2
	v_lshlrev_b32_e32 v4, 2, v240
	v_lshl_or_b32 v200, s6, 6, v1
	v_lshl_or_b32 v1, v1, 6, v0
	v_and_b32_e32 v4, 32, v4
	v_bitop3_b32 v5, v1, s3, v4 bitop3:0xde
	v_bitop3_b32 v201, s4, v1, v4 bitop3:0xf6
	v_mov_b32_e32 v1, v131
	v_lshl_add_u64 v[136:137], s[14:15], 0, v[0:1]
	v_lshrrev_b32_e32 v1, 1, v8
	v_mul_lo_u32 v0, v10, s2
	s_mov_b32 s3, 0xb000
	v_mad_u64_u32 v[0:1], s[6:7], v1, s3, v[0:1]
	v_or_b32_e32 v0, v0, v9
	s_mov_b64 s[4:5], 0xb0080
	v_add_lshl_u32 v0, v0, v11, 1
	v_mov_b32_e32 v1, v131
	v_lshl_add_u64 v[138:139], v[0:1], 0, s[4:5]
	v_lshrrev_b32_e32 v1, 1, v12
	v_mul_lo_u32 v0, v13, s2
	v_mad_u64_u32 v[0:1], s[2:3], v1, s3, v[0:1]
	s_waitcnt vmcnt(6)
	v_or_b32_e32 v0, v0, v14
	v_lshlrev_b32_e32 v3, 3, v2
	v_add_lshl_u32 v0, v0, v15, 1
	v_mov_b32_e32 v1, v131
	s_add_i32 s47, 0, 0x10000
	s_add_i32 s48, 0, 0x14000
	v_lshl_or_b32 v202, s41, 5, v3
	v_cmp_eq_u32_e64 s[0:1], 0, v2
	s_ashr_i32 s44, s29, 31
	s_ashr_i32 s45, s28, 31
	v_lshl_add_u64 v[140:141], v[0:1], 0, s[4:5]
	v_mov_b64_e32 v[142:143], 0x300
	v_mov_b64_e32 v[144:145], 0x2ff
	s_movk_i32 s46, 0x61
	v_add_u32_e32 v203, s47, v201
	v_add_u32_e32 v204, 0, v5
	v_add_u32_e32 v205, s48, v201
	v_mbcnt_hi_u32_b32 v206, -1, v241
	v_mov_b32_e32 v207, 0x358637bd
	s_mov_b32 s49, 0x800000
	s_mov_b32 s50, 0
	s_barrier
	s_branch .LBB0_966

.Lg973_noy:
	ds_read_b128 v[146:149], v203
	ds_read_b128 v[150:153], v203 offset:1024
	ds_read_b128 v[154:157], v203 offset:2048
	ds_read_b128 v[158:161], v203 offset:3072
	s_add_u32 s22, s20, 0x100
	s_addc_u32 s23, s21, 0
	s_cmp_eq_u32 s56, 40
	s_cselect_b32 s27, s5, s23
	s_cselect_b32 s26, s4, s22
	s_cselect_b32 s25, s7, s55
	s_cselect_b32 s24, s6, s54
	s_add_i32 m0, s37, 0xc000
	ds_read_b128 v[162:165], v204
	ds_read_b128 v[166:169], v204 offset:1024
	ds_read_b128 v[170:173], v204 offset:2048
	ds_read_b128 v[174:177], v204 offset:3072
	ds_read_b128 v[178:181], v204 offset:4096
	ds_read_b128 v[182:185], v204 offset:5120
	ds_read_b128 v[186:189], v204 offset:6144
	ds_read_b128 v[190:193], v204 offset:7168
	global_load_lds_dwordx4 v138, s[20:21]
	s_add_i32 m0, s37, 0xe000
	s_nop 0
	global_load_lds_dwordx4 v140, s[20:21]
	s_waitcnt lgkmcnt(8)
	s_barrier
	s_waitcnt lgkmcnt(0)
	s_waitcnt lgkmcnt(0)
	v_mfma_f32_16x16x32_bf16 v[124:127], v[146:149], v[162:165], 0
	v_mfma_f32_16x16x32_bf16 v[120:123], v[154:157], v[162:165], 0
	v_mfma_f32_16x16x32_bf16 v[108:111], v[146:149], v[170:173], 0
	v_mfma_f32_16x16x32_bf16 v[104:107], v[154:157], v[170:173], 0
	v_mfma_f32_16x16x32_bf16 v[92:95], v[146:149], v[178:181], 0
	v_mfma_f32_16x16x32_bf16 v[88:91], v[154:157], v[178:181], 0
	v_mfma_f32_16x16x32_bf16 v[76:79], v[146:149], v[186:189], 0
	v_mfma_f32_16x16x32_bf16 v[72:75], v[154:157], v[186:189], 0
	v_mfma_f32_16x16x32_bf16 v[124:127], v[150:153], v[166:169], v[124:127]
	v_mfma_f32_16x16x32_bf16 v[120:123], v[158:161], v[166:169], v[120:123]
	v_mfma_f32_16x16x32_bf16 v[108:111], v[150:153], v[174:177], v[108:111]
	v_mfma_f32_16x16x32_bf16 v[104:107], v[158:161], v[174:177], v[104:107]
	v_mfma_f32_16x16x32_bf16 v[92:95], v[150:153], v[182:185], v[92:95]
	v_mfma_f32_16x16x32_bf16 v[88:91], v[158:161], v[182:185], v[88:91]
	v_mfma_f32_16x16x32_bf16 v[76:79], v[150:153], v[190:193], v[76:79]
	v_mfma_f32_16x16x32_bf16 v[72:75], v[158:161], v[190:193], v[72:75]
	s_barrier
	s_add_i32 s20, s47, s36
	s_add_u32 s80, s24, 0x80
	s_addc_u32 s81, s25, 0
	s_mov_b32 m0, s20
	ds_read_b128 v[194:197], v205
	ds_read_b128 v[208:211], v205 offset:1024
	ds_read_b128 v[212:215], v205 offset:2048
	ds_read_b128 v[216:219], v205 offset:3072
	global_load_lds_dwordx4 v130, s[24:25]
	s_add_i32 m0, s20, 0x2000
	s_nop 0
	global_load_lds_dwordx4 v134, s[24:25]
	s_cmp_lg_u32 s94, 0
	s_cbranch_scc1 .Lpw973_0a
	s_waitcnt vmcnt(10)
	s_branch .Lpw973_0b
.Lpw973_0a:
	s_waitcnt vmcnt(42)
.Lpw973_0b:
	s_barrier
	s_waitcnt lgkmcnt(0)
	s_waitcnt lgkmcnt(0)
	v_mfma_f32_16x16x32_bf16 v[116:119], v[194:197], v[162:165], 0
	v_mfma_f32_16x16x32_bf16 v[112:115], v[212:215], v[162:165], 0
	v_mfma_f32_16x16x32_bf16 v[100:103], v[194:197], v[170:173], 0
	v_mfma_f32_16x16x32_bf16 v[96:99], v[212:215], v[170:173], 0
	v_mfma_f32_16x16x32_bf16 v[84:87], v[194:197], v[178:181], 0
	v_mfma_f32_16x16x32_bf16 v[80:83], v[212:215], v[178:181], 0
	v_mfma_f32_16x16x32_bf16 v[68:71], v[194:197], v[186:189], 0
	v_mfma_f32_16x16x32_bf16 v[64:67], v[212:215], v[186:189], 0
	v_mfma_f32_16x16x32_bf16 v[116:119], v[208:211], v[166:169], v[116:119]
	v_mfma_f32_16x16x32_bf16 v[112:115], v[216:219], v[166:169], v[112:115]
	v_mfma_f32_16x16x32_bf16 v[100:103], v[208:211], v[174:177], v[100:103]
	v_mfma_f32_16x16x32_bf16 v[96:99], v[216:219], v[174:177], v[96:99]
	v_mfma_f32_16x16x32_bf16 v[84:87], v[208:211], v[182:185], v[84:87]
	v_mfma_f32_16x16x32_bf16 v[80:83], v[216:219], v[182:185], v[80:83]
	v_mfma_f32_16x16x32_bf16 v[68:71], v[208:211], v[190:193], v[68:71]
	v_mfma_f32_16x16x32_bf16 v[64:67], v[216:219], v[190:193], v[64:67]
	s_mov_b32 m0, s37
	s_add_u32 s82, s26, 0x80
	s_addc_u32 s83, s27, 0
	s_barrier
	ds_read_b128 v[162:165], v204 offset:16384
	ds_read_b128 v[166:169], v204 offset:17408
	ds_read_b128 v[170:173], v204 offset:18432
	ds_read_b128 v[174:177], v204 offset:19456
	ds_read_b128 v[178:181], v204 offset:20480
	ds_read_b128 v[182:185], v204 offset:21504
	ds_read_b128 v[186:189], v204 offset:22528
	ds_read_b128 v[190:193], v204 offset:23552
	global_load_lds_dwordx4 v128, s[26:27]
	s_mov_b32 m0, s38
	s_nop 0
	global_load_lds_dwordx4 v132, s[26:27]
	s_barrier
	s_waitcnt lgkmcnt(0)
	s_waitcnt lgkmcnt(0)
	v_mfma_f32_16x16x32_bf16 v[60:63], v[146:149], v[162:165], 0
	v_mfma_f32_16x16x32_bf16 v[56:59], v[154:157], v[162:165], 0
	v_mfma_f32_16x16x32_bf16 v[44:47], v[146:149], v[170:173], 0
	v_mfma_f32_16x16x32_bf16 v[40:43], v[154:157], v[170:173], 0
	v_mfma_f32_16x16x32_bf16 v[28:31], v[146:149], v[178:181], 0
	v_mfma_f32_16x16x32_bf16 v[24:27], v[154:157], v[178:181], 0
	v_mfma_f32_16x16x32_bf16 v[12:15], v[146:149], v[186:189], 0
	v_mfma_f32_16x16x32_bf16 v[8:11], v[154:157], v[186:189], 0
	v_mfma_f32_16x16x32_bf16 v[60:63], v[150:153], v[166:169], v[60:63]
	v_mfma_f32_16x16x32_bf16 v[56:59], v[158:161], v[166:169], v[56:59]
	v_mfma_f32_16x16x32_bf16 v[44:47], v[150:153], v[174:177], v[44:47]
	v_mfma_f32_16x16x32_bf16 v[40:43], v[158:161], v[174:177], v[40:43]
	v_mfma_f32_16x16x32_bf16 v[28:31], v[150:153], v[182:185], v[28:31]
	v_mfma_f32_16x16x32_bf16 v[24:27], v[158:161], v[182:185], v[24:27]
	v_mfma_f32_16x16x32_bf16 v[12:15], v[150:153], v[190:193], v[12:15]
	v_mfma_f32_16x16x32_bf16 v[8:11], v[158:161], v[190:193], v[8:11]
	s_barrier
	s_add_u32 s20, s24, 0xb0000
	s_addc_u32 s21, s25, 0
	s_add_i32 s57, s48, s36
	s_mov_b32 m0, s57
	s_nop 0
	global_load_lds_dwordx4 v130, s[20:21]
	s_add_i32 m0, s57, 0x2000
	s_nop 0
	global_load_lds_dwordx4 v134, s[20:21]
	s_cmp_lg_u32 s94, 0
	s_cbranch_scc1 .Lpw973_1a
	s_waitcnt vmcnt(8)
	s_branch .Lpw973_1b
.Lpw973_1a:
	s_waitcnt vmcnt(40)
.Lpw973_1b:
	s_barrier
	v_mfma_f32_16x16x32_bf16 v[52:55], v[194:197], v[162:165], 0
	v_mfma_f32_16x16x32_bf16 v[48:51], v[212:215], v[162:165], 0
	v_mfma_f32_16x16x32_bf16 v[36:39], v[194:197], v[170:173], 0
	v_mfma_f32_16x16x32_bf16 v[32:35], v[212:215], v[170:173], 0
	v_mfma_f32_16x16x32_bf16 v[20:23], v[194:197], v[178:181], 0
	v_mfma_f32_16x16x32_bf16 v[16:19], v[212:215], v[178:181], 0
	v_mfma_f32_16x16x32_bf16 v[4:7], v[194:197], v[186:189], 0
	v_mfma_f32_16x16x32_bf16 v[0:3], v[212:215], v[186:189], 0
	v_mfma_f32_16x16x32_bf16 v[52:55], v[208:211], v[166:169], v[52:55]
	v_mfma_f32_16x16x32_bf16 v[48:51], v[216:219], v[166:169], v[48:51]
	v_mfma_f32_16x16x32_bf16 v[36:39], v[208:211], v[174:177], v[36:39]
	v_mfma_f32_16x16x32_bf16 v[32:35], v[216:219], v[174:177], v[32:35]
	v_mfma_f32_16x16x32_bf16 v[20:23], v[208:211], v[182:185], v[20:23]
	v_mfma_f32_16x16x32_bf16 v[16:19], v[216:219], v[182:185], v[16:19]
	v_mfma_f32_16x16x32_bf16 v[4:7], v[208:211], v[190:193], v[4:7]
	v_mfma_f32_16x16x32_bf16 v[0:3], v[216:219], v[190:193], v[0:3]
	s_add_i32 s57, 0, 0x18000
	v_add_u32_e32 v158, s57, v201
	s_barrier
	s_branch .Lg973_mid

.Lg973_nox:
	s_mov_b32 s94, 1
	v_lshl_add_u32 v148, s53, 8, v200
	v_ashrrev_i32_e32 v149, 31, v148
	v_lshl_or_b32 v146, s10, 8, v202
	v_lshlrev_b64 v[150:151], 11, v[148:149]
	v_ashrrev_i32_e32 v147, 31, v146
	v_lshl_add_u64 v[150:151], s[12:13], 0, v[150:151]
	v_lshl_add_u64 v[154:155], v[146:147], 1, v[150:151]
	global_load_dwordx4 v[150:153], v[154:155], off
	s_nop 0
	global_load_dwordx4 v[154:157], v[154:155], off offset:256
	v_and_b32_e32 v159, 64, v206
	v_xor_b32_e32 v158, 16, v206
	v_add_u32_e32 v166, 64, v159
	v_cmp_lt_i32_e32 vcc, v158, v166
	s_lshl_b32 s20, s10, 2
	s_ashr_i32 s21, s20, 31
	v_cndmask_b32_e32 v158, v206, v158, vcc
	v_lshlrev_b32_e32 v208, 2, v158
	v_lshlrev_b64 v[182:183], 6, v[148:149]
	s_waitcnt vmcnt(0)
	v_lshlrev_b32_e32 v158, 16, v150
	v_and_b32_e32 v159, 0xffff0000, v150
	v_lshlrev_b32_e32 v150, 16, v151
	v_and_b32_e32 v151, 0xffff0000, v151
	v_lshlrev_b32_e32 v160, 16, v152
	v_and_b32_e32 v161, 0xffff0000, v152
	v_lshlrev_b32_e32 v162, 16, v154
	v_and_b32_e32 v163, 0xffff0000, v154
	v_lshlrev_b32_e32 v154, 16, v155
	v_and_b32_e32 v155, 0xffff0000, v155
	v_lshlrev_b32_e32 v164, 16, v156
	v_and_b32_e32 v165, 0xffff0000, v156
	v_pk_fma_f32 v[126:127], v[126:127], 0.5, v[150:151] op_sel_hi:[1,0,1]
	v_pk_fma_f32 v[150:151], v[124:125], 0.5, v[158:159] op_sel_hi:[1,0,1]
	v_pk_fma_f32 v[124:125], v[120:121], 0.5, v[160:161] op_sel_hi:[1,0,1]
	v_pk_fma_f32 v[118:119], v[118:119], 0.5, v[154:155] op_sel_hi:[1,0,1]
	v_pk_fma_f32 v[120:121], v[116:117], 0.5, v[162:163] op_sel_hi:[1,0,1]
	v_lshlrev_b32_e32 v152, 16, v153
	v_and_b32_e32 v153, 0xffff0000, v153
	v_lshlrev_b32_e32 v156, 16, v157
	v_and_b32_e32 v157, 0xffff0000, v157
	v_pk_fma_f32 v[116:117], v[112:113], 0.5, v[164:165] op_sel_hi:[1,0,1]
	v_mul_f32_e32 v112, v151, v151
	v_mul_f32_e32 v113, v127, v127
	v_mul_f32_e32 v154, v121, v121
	v_mul_f32_e32 v155, v119, v119
	v_pk_fma_f32 v[122:123], v[122:123], 0.5, v[152:153] op_sel_hi:[1,0,1]
	v_pk_fma_f32 v[114:115], v[114:115], 0.5, v[156:157] op_sel_hi:[1,0,1]
	v_mul_f32_e32 v152, v125, v125
	v_mul_f32_e32 v156, v117, v117
	v_fmac_f32_e32 v112, v150, v150
	v_fmac_f32_e32 v113, v126, v126
	v_fmac_f32_e32 v154, v120, v120
	v_fmac_f32_e32 v155, v118, v118
	v_mul_f32_e32 v153, v123, v123
	v_mul_f32_e32 v157, v115, v115
	v_fmac_f32_e32 v152, v124, v124
	v_fmac_f32_e32 v156, v116, v116
	v_add_f32_e32 v112, v112, v113
	v_add_f32_e32 v113, v154, v155
	v_fmac_f32_e32 v153, v122, v122
	v_fmac_f32_e32 v157, v114, v114
	v_add_f32_e32 v112, v152, v112
	v_add_f32_e32 v113, v156, v113
	v_add_f32_e32 v112, v153, v112
	v_add_f32_e32 v113, v157, v113
	v_add_f32_e32 v112, v112, v113
	ds_bpermute_b32 v113, v208, v112
	v_xor_b32_e32 v152, 32, v206
	v_cmp_lt_i32_e32 vcc, v152, v166
	s_waitcnt lgkmcnt(0)
	v_add_f32_e32 v112, v112, v113
	v_cndmask_b32_e32 v152, v206, v152, vcc
	v_lshlrev_b32_e32 v209, 2, v152
	ds_bpermute_b32 v113, v209, v112
	s_and_saveexec_b64 s[22:23], s[0:1]
	s_cbranch_execz .LBB0_976
	s_waitcnt lgkmcnt(0)
	v_add_f32_e32 v152, v112, v113
	v_lshl_add_u64 v[112:113], s[14:15], 0, v[182:183]
	v_lshl_add_u64 v[112:113], s[20:21], 2, v[112:113]
	s_lshl_b32 s10, s41, 2
	v_lshl_add_u64 v[112:113], v[112:113], 0, s[10:11]
	global_store_dword v[112:113], v152, off sc1
